# v30
# speedup vs baseline: 1.0051x; 1.0051x over previous
.LBB0_499:
	s_andn2_saveexec_b64 s[12:13], s[28:29]
	s_cbranch_execz .LBB0_534
	s_cmp_eq_u32 s26, -16
	s_cbranch_scc1 .LBB0_534
	s_bitcmp1_b32 s34, 0
	s_cselect_b32 s28, 0x5180, 0
	v_add_u32_e32 v50, s28, v72
	v_lshl_add_u32 v59, v74, 2, v50
	s_waitcnt lgkmcnt(0)
	ds_read_b128 v[34:37], v59
	ds_read_b128 v[38:41], v59 offset:32
	ds_read_b128 v[42:45], v59 offset:768
	ds_read_b128 v[162:165], v59 offset:800
	ds_read_b128 v[166:169], v59 offset:64
	ds_read_b128 v[170:173], v59 offset:96
	ds_read_b128 v[174:177], v59 offset:832
	ds_read_b128 v[178:181], v59 offset:864
	ds_read_b128 v[182:185], v59 offset:128
	ds_read_b128 v[186:189], v59 offset:160
	ds_read_b128 v[190:193], v59 offset:192
	ds_read_b128 v[194:197], v59 offset:224
	s_waitcnt lgkmcnt(11)
	v_pk_fma_f32 v[36:37], v[2:3], v[36:37], 0 op_sel_hi:[1,1,0]
	v_pk_fma_f32 v[34:35], v[0:1], v[34:35], 0 op_sel_hi:[1,1,0]
	s_waitcnt lgkmcnt(3)
	v_pk_fma_f32 v[46:47], v[18:19], v[184:185], 0 op_sel_hi:[1,1,0]
	v_pk_fma_f32 v[182:183], v[16:17], v[182:183], 0 op_sel_hi:[1,1,0]
	v_pk_fma_f32 v[36:37], v[6:7], v[40:41], v[36:37]
	v_pk_fma_f32 v[34:35], v[4:5], v[38:39], v[34:35]
	s_waitcnt lgkmcnt(2)
	v_pk_fma_f32 v[38:39], v[22:23], v[188:189], v[46:47]
	v_lshl_add_u32 v61, v102, 2, v50
	v_pk_fma_f32 v[40:41], v[20:21], v[186:187], v[182:183]
	v_pk_fma_f32 v[36:37], v[10:11], v[168:169], v[36:37]
	v_pk_fma_f32 v[34:35], v[8:9], v[166:167], v[34:35]
	s_waitcnt lgkmcnt(1)
	v_pk_fma_f32 v[38:39], v[26:27], v[192:193], v[38:39]
	ds_read2_b32 v[198:199], v61 offset0:64 offset1:96
	v_pk_fma_f32 v[40:41], v[24:25], v[190:191], v[40:41]
	v_pk_fma_f32 v[36:37], v[14:15], v[172:173], v[36:37]
	v_pk_fma_f32 v[34:35], v[12:13], v[170:171], v[34:35]
	s_waitcnt lgkmcnt(1)
	v_pk_fma_f32 v[38:39], v[30:31], v[196:197], v[38:39]
	v_pk_fma_f32 v[40:41], v[28:29], v[194:195], v[40:41]
	v_add_f32_e32 v32, v34, v35
	v_add_f32_e32 v34, v36, v37
	v_add_f32_e32 v35, v38, v39
	v_pk_fma_f32 v[36:37], v[2:3], v[44:45], 0 op_sel_hi:[1,1,0]
	v_pk_fma_f32 v[38:39], v[0:1], v[42:43], 0 op_sel_hi:[1,1,0]
	v_lshl_add_u32 v158, v75, 2, v50
	v_add_f32_e32 v32, v32, v34
	v_add_f32_e32 v34, v40, v41
	v_pk_fma_f32 v[36:37], v[6:7], v[164:165], v[36:37]
	v_pk_fma_f32 v[38:39], v[4:5], v[162:163], v[38:39]
	ds_read_b32 v33, v158 offset:1024
	ds_read_b64 v[170:171], v50 offset:20736
	v_add_f32_e32 v34, v34, v35
	v_pk_fma_f32 v[36:37], v[10:11], v[176:177], v[36:37]
	v_pk_fma_f32 v[38:39], v[8:9], v[174:175], v[38:39]
	v_add_f32_e32 v32, v32, v34
	v_pk_fma_f32 v[166:167], v[14:15], v[180:181], v[36:37]
	v_pk_fma_f32 v[168:169], v[12:13], v[178:179], v[38:39]
	ds_read_b128 v[36:39], v59 offset:896
	ds_read_b128 v[40:43], v59 offset:928
	ds_read_b128 v[44:47], v59 offset:960
	ds_read_b128 v[162:165], v59 offset:992
	v_mov_b32_e32 v34, v32
	s_nop 1
	v_permlane32_swap_b32_e32 v32, v34
	s_waitcnt lgkmcnt(3)
	v_pk_fma_f32 v[38:39], v[18:19], v[38:39], 0 op_sel_hi:[1,1,0]
	v_pk_fma_f32 v[36:37], v[16:17], v[36:37], 0 op_sel_hi:[1,1,0]
	v_add_f32_e32 v35, v32, v34
	s_waitcnt lgkmcnt(2)
	v_pk_fma_f32 v[38:39], v[22:23], v[42:43], v[38:39]
	v_pk_fma_f32 v[36:37], v[20:21], v[40:41], v[36:37]
	v_cndmask_b32_e64 v32, v33, v35, s[6:7]
	s_waitcnt lgkmcnt(1)
	v_pk_fma_f32 v[38:39], v[26:27], v[46:47], v[38:39]
	v_pk_fma_f32 v[36:37], v[24:25], v[44:45], v[36:37]
	v_mfma_f32_32x32x2_f32 v[0:15], v198, v32, v[0:15]
	s_waitcnt lgkmcnt(0)
	v_pk_fma_f32 v[38:39], v[30:31], v[164:165], v[38:39]
	v_pk_fma_f32 v[36:37], v[28:29], v[162:163], v[36:37]
	v_add_f32_e32 v34, v166, v167
	v_mfma_f32_32x32x2_f32 v[16:31], v199, v32, v[16:31]
	v_add_f32_e32 v32, v168, v169
	v_add_f32_e32 v32, v32, v34
	v_add_f32_e32 v34, v36, v37
	v_add_f32_e32 v36, v38, v39
	v_add_f32_e32 v34, v34, v36
	v_add_f32_e32 v32, v32, v34
	v_mov_b32_e32 v34, v32
	s_nop 1
	v_permlane32_swap_b32_e32 v32, v34
	s_and_saveexec_b64 s[28:29], s[6:7]
	s_cbranch_execz .LBB0_503
	s_add_i32 s39, s30, 39
	s_and_b64 s[34:35], s[8:9], exec
	s_cselect_b32 s34, s26, s39
	s_ashr_i32 s35, s34, 31
	s_waitcnt lgkmcnt(0)
	v_mul_f32_e32 v35, v35, v170
	v_mul_f32_e32 v33, v33, v171
	v_pk_add_f32 v[32:33], v[32:33], v[34:35]
	s_nop 0
	v_add_f32_e32 v34, v32, v33
	v_lshl_add_u64 v[32:33], v[66:67], 0, s[34:35]
	v_lshlrev_b64 v[32:33], 11, v[32:33]
	v_lshl_add_u64 v[32:33], v[68:69], 0, v[32:33]
	global_store_dword v[32:33], v34, off
.LBB0_503:
	s_or_b64 exec, exec, s[28:29]
	ds_read_b128 v[32:35], v59 offset:1280
	ds_read_b128 v[36:39], v59 offset:1312
	ds_read_b128 v[162:165], v59 offset:2048
	ds_read_b128 v[166:169], v59 offset:2080
	ds_read_b128 v[40:43], v59 offset:1344
	ds_read_b128 v[44:47], v59 offset:1376
	ds_read_b128 v[170:173], v59 offset:2112
	ds_read_b128 v[174:177], v59 offset:2144
	ds_read_b128 v[178:181], v59 offset:1408
	ds_read_b128 v[182:185], v59 offset:1440
	ds_read_b128 v[186:189], v59 offset:2176
	ds_read_b128 v[190:193], v59 offset:2208
	ds_read_b128 v[194:197], v59 offset:1472
	ds_read_b128 v[198:201], v59 offset:1504
	ds_read_b128 v[202:205], v59 offset:2240
	ds_read_b128 v[206:209], v59 offset:2272
	s_waitcnt lgkmcnt(14)
	v_pk_fma_f32 v[34:35], v[2:3], v[34:35], 0 op_sel_hi:[1,1,0]
	v_pk_fma_f32 v[32:33], v[0:1], v[32:33], 0 op_sel_hi:[1,1,0]
	s_waitcnt lgkmcnt(7)
	v_pk_fma_f32 v[180:181], v[18:19], v[180:181], 0 op_sel_hi:[1,1,0]
	v_pk_fma_f32 v[178:179], v[16:17], v[178:179], 0 op_sel_hi:[1,1,0]
	v_pk_fma_f32 v[34:35], v[6:7], v[38:39], v[34:35]
	v_pk_fma_f32 v[32:33], v[4:5], v[36:37], v[32:33]
	s_waitcnt lgkmcnt(6)
	v_pk_fma_f32 v[36:37], v[22:23], v[184:185], v[180:181]
	v_pk_fma_f32 v[38:39], v[20:21], v[182:183], v[178:179]
	v_pk_fma_f32 v[32:33], v[8:9], v[40:41], v[32:33]
	v_pk_fma_f32 v[34:35], v[10:11], v[42:43], v[34:35]
	s_waitcnt lgkmcnt(3)
	v_pk_fma_f32 v[38:39], v[24:25], v[194:195], v[38:39]
	v_pk_fma_f32 v[36:37], v[26:27], v[196:197], v[36:37]
	v_pk_fma_f32 v[34:35], v[14:15], v[46:47], v[34:35]
	v_pk_fma_f32 v[32:33], v[12:13], v[44:45], v[32:33]
	s_waitcnt lgkmcnt(2)
	v_pk_fma_f32 v[36:37], v[30:31], v[200:201], v[36:37]
	v_pk_fma_f32 v[38:39], v[28:29], v[198:199], v[38:39]
	v_add_f32_e32 v32, v32, v33
	v_add_f32_e32 v33, v34, v35
	v_add_u32_e32 v159, 0x400, v61
	v_add_f32_e32 v32, v32, v33
	v_add_f32_e32 v33, v38, v39
	v_add_f32_e32 v34, v36, v37
	ds_read2_b32 v[210:211], v159 offset0:128 offset1:160
	ds_read_b32 v159, v158 offset:2304
	ds_read_b64 v[194:195], v50 offset:20744
	v_add_f32_e32 v33, v33, v34
	v_add_f32_e32 v32, v32, v33
	v_mov_b32_e32 v33, v32
	s_nop 1
	v_permlane32_swap_b32_e32 v32, v33
	v_add_f32_e32 v161, v32, v33
	s_waitcnt lgkmcnt(0)
	v_cndmask_b32_e64 v178, v159, v161, s[6:7]
	v_pk_fma_f32 v[164:165], v[2:3], v[164:165], 0 op_sel_hi:[1,1,0]
	v_pk_fma_f32 v[162:163], v[0:1], v[162:163], 0 op_sel_hi:[1,1,0]
	v_mfma_f32_32x32x2_f32 v[32:47], v211, v178, v[16:31]
	v_pk_fma_f32 v[18:19], v[18:19], v[188:189], 0 op_sel_hi:[1,1,0]
	v_pk_fma_f32 v[16:17], v[16:17], v[186:187], 0 op_sel_hi:[1,1,0]
	v_pk_fma_f32 v[164:165], v[6:7], v[168:169], v[164:165]
	v_pk_fma_f32 v[162:163], v[4:5], v[166:167], v[162:163]
	v_pk_fma_f32 v[18:19], v[22:23], v[192:193], v[18:19]
	v_pk_fma_f32 v[16:17], v[20:21], v[190:191], v[16:17]
	v_pk_fma_f32 v[20:21], v[8:9], v[170:171], v[162:163]
	v_pk_fma_f32 v[22:23], v[10:11], v[172:173], v[164:165]
	v_pk_fma_f32 v[20:21], v[12:13], v[174:175], v[20:21]
	v_pk_fma_f32 v[22:23], v[14:15], v[176:177], v[22:23]
	v_pk_fma_f32 v[16:17], v[24:25], v[202:203], v[16:17]
	v_pk_fma_f32 v[18:19], v[26:27], v[204:205], v[18:19]
	v_pk_fma_f32 v[16:17], v[28:29], v[206:207], v[16:17]
	v_pk_fma_f32 v[18:19], v[30:31], v[208:209], v[18:19]
	v_add_f32_e32 v20, v20, v21
	v_mfma_f32_32x32x2_f32 v[0:15], v210, v178, v[0:15]
	v_add_f32_e32 v21, v22, v23
	v_add_f32_e32 v16, v16, v17
	v_add_f32_e32 v17, v18, v19
	v_add_f32_e32 v20, v20, v21
	v_add_f32_e32 v16, v16, v17
	v_add_f32_e32 v16, v20, v16
	v_mov_b32_e32 v18, v16
	s_nop 1
	v_permlane32_swap_b32_e32 v16, v18
	s_and_saveexec_b64 s[28:29], s[6:7]
	s_cbranch_execz .LBB0_505
	s_add_i32 s39, s26, 1
	s_add_i32 s41, s30, 38
	s_and_b64 s[34:35], s[8:9], exec
	s_cselect_b32 s34, s39, s41
	s_waitcnt lgkmcnt(0)
	v_mul_f32_e32 v19, v161, v194
	v_mul_f32_e32 v17, v159, v195
	v_pk_add_f32 v[16:17], v[16:17], v[18:19]
	s_ashr_i32 s35, s34, 31
	v_add_f32_e32 v18, v16, v17
	v_lshl_add_u64 v[16:17], v[66:67], 0, s[34:35]
	v_lshlrev_b64 v[16:17], 11, v[16:17]
	v_lshl_add_u64 v[16:17], v[68:69], 0, v[16:17]
	global_store_dword v[16:17], v18, off
.LBB0_505:
	s_or_b64 exec, exec, s[28:29]
	ds_read_b128 v[18:21], v59 offset:2560
	ds_read_b128 v[22:25], v59 offset:2592
	ds_read_b128 v[26:29], v59 offset:3328
	ds_read_b128 v[162:165], v59 offset:3360
	ds_read_b128 v[166:169], v59 offset:2624
	ds_read_b128 v[170:173], v59 offset:2656
	ds_read_b128 v[174:177], v59 offset:3392
	ds_read_b128 v[178:181], v59 offset:3424
	ds_read_b128 v[182:185], v59 offset:2688
	ds_read_b128 v[186:189], v59 offset:2720
	ds_read_b128 v[190:193], v59 offset:2752
	ds_read_b128 v[194:197], v59 offset:2784
	s_waitcnt lgkmcnt(11)
	v_pk_fma_f32 v[20:21], v[2:3], v[20:21], 0 op_sel_hi:[1,1,0]
	v_pk_fma_f32 v[18:19], v[0:1], v[18:19], 0 op_sel_hi:[1,1,0]
	s_waitcnt lgkmcnt(3)
	v_pk_fma_f32 v[30:31], v[34:35], v[184:185], 0 op_sel_hi:[1,1,0]
	v_pk_fma_f32 v[182:183], v[32:33], v[182:183], 0 op_sel_hi:[1,1,0]
	v_pk_fma_f32 v[20:21], v[6:7], v[24:25], v[20:21]
	v_pk_fma_f32 v[18:19], v[4:5], v[22:23], v[18:19]
	s_waitcnt lgkmcnt(2)
	v_pk_fma_f32 v[22:23], v[38:39], v[188:189], v[30:31]
	v_pk_fma_f32 v[24:25], v[36:37], v[186:187], v[182:183]
	v_pk_fma_f32 v[18:19], v[8:9], v[166:167], v[18:19]
	v_pk_fma_f32 v[20:21], v[10:11], v[168:169], v[20:21]
	s_waitcnt lgkmcnt(1)
	v_pk_fma_f32 v[22:23], v[42:43], v[192:193], v[22:23]
	v_add_u32_e32 v16, 0x800, v61
	v_pk_fma_f32 v[24:25], v[40:41], v[190:191], v[24:25]
	v_pk_fma_f32 v[20:21], v[14:15], v[172:173], v[20:21]
	v_pk_fma_f32 v[18:19], v[12:13], v[170:171], v[18:19]
	s_waitcnt lgkmcnt(0)
	v_pk_fma_f32 v[22:23], v[46:47], v[196:197], v[22:23]
	ds_read2_b32 v[198:199], v16 offset0:192 offset1:224
	ds_read_b32 v17, v158 offset:3584
	ds_read_b64 v[170:171], v50 offset:20752
	v_pk_fma_f32 v[24:25], v[44:45], v[194:195], v[24:25]
	v_add_f32_e32 v16, v18, v19
	v_add_f32_e32 v18, v20, v21
	v_add_f32_e32 v19, v22, v23
	v_pk_fma_f32 v[20:21], v[2:3], v[28:29], 0 op_sel_hi:[1,1,0]
	v_pk_fma_f32 v[22:23], v[0:1], v[26:27], 0 op_sel_hi:[1,1,0]
	v_add_f32_e32 v16, v16, v18
	v_add_f32_e32 v18, v24, v25
	v_pk_fma_f32 v[20:21], v[6:7], v[164:165], v[20:21]
	v_pk_fma_f32 v[22:23], v[4:5], v[162:163], v[22:23]
	v_add_f32_e32 v18, v18, v19
	v_pk_fma_f32 v[22:23], v[8:9], v[174:175], v[22:23]
	v_pk_fma_f32 v[20:21], v[10:11], v[176:177], v[20:21]
	v_add_f32_e32 v16, v16, v18
	v_pk_fma_f32 v[166:167], v[14:15], v[180:181], v[20:21]
	v_pk_fma_f32 v[168:169], v[12:13], v[178:179], v[22:23]
	ds_read_b128 v[20:23], v59 offset:3456
	ds_read_b128 v[24:27], v59 offset:3488
	ds_read_b128 v[28:31], v59 offset:3520
	ds_read_b128 v[162:165], v59 offset:3552
	v_mov_b32_e32 v18, v16
	s_nop 1
	v_permlane32_swap_b32_e32 v16, v18
	s_waitcnt lgkmcnt(3)
	v_pk_fma_f32 v[22:23], v[34:35], v[22:23], 0 op_sel_hi:[1,1,0]
	v_pk_fma_f32 v[20:21], v[32:33], v[20:21], 0 op_sel_hi:[1,1,0]
	v_add_f32_e32 v19, v16, v18
	s_waitcnt lgkmcnt(2)
	v_pk_fma_f32 v[22:23], v[38:39], v[26:27], v[22:23]
	v_pk_fma_f32 v[20:21], v[36:37], v[24:25], v[20:21]
	v_cndmask_b32_e64 v16, v17, v19, s[6:7]
	s_waitcnt lgkmcnt(1)
	v_pk_fma_f32 v[20:21], v[40:41], v[28:29], v[20:21]
	v_pk_fma_f32 v[22:23], v[42:43], v[30:31], v[22:23]
	v_mfma_f32_32x32x2_f32 v[0:15], v198, v16, v[0:15]
	s_waitcnt lgkmcnt(0)
	v_pk_fma_f32 v[22:23], v[46:47], v[164:165], v[22:23]
	v_pk_fma_f32 v[20:21], v[44:45], v[162:163], v[20:21]
	v_add_f32_e32 v18, v166, v167
	v_mfma_f32_32x32x2_f32 v[32:47], v199, v16, v[32:47]
	v_add_f32_e32 v16, v168, v169
	v_add_f32_e32 v16, v16, v18
	v_add_f32_e32 v18, v20, v21
	v_add_f32_e32 v20, v22, v23
	v_add_f32_e32 v18, v18, v20
	v_add_f32_e32 v16, v16, v18
	v_mov_b32_e32 v18, v16
	s_nop 1
	v_permlane32_swap_b32_e32 v16, v18
	s_and_saveexec_b64 s[28:29], s[6:7]
	s_cbranch_execz .LBB0_507
	s_add_i32 s39, s26, 2
	s_add_i32 s41, s30, 37
	s_and_b64 s[34:35], s[8:9], exec
	s_cselect_b32 s34, s39, s41
	s_waitcnt lgkmcnt(0)
	v_mul_f32_e32 v19, v19, v170
	v_mul_f32_e32 v17, v17, v171
	v_pk_add_f32 v[16:17], v[16:17], v[18:19]
	s_ashr_i32 s35, s34, 31
	v_add_f32_e32 v18, v16, v17
	v_lshl_add_u64 v[16:17], v[66:67], 0, s[34:35]
	v_lshlrev_b64 v[16:17], 11, v[16:17]
	v_lshl_add_u64 v[16:17], v[68:69], 0, v[16:17]
	global_store_dword v[16:17], v18, off
.LBB0_507:
	s_or_b64 exec, exec, s[28:29]
	ds_read_b128 v[16:19], v59 offset:3840
	ds_read_b128 v[20:23], v59 offset:3872
	ds_read_b128 v[162:165], v59 offset:4608
	ds_read_b128 v[166:169], v59 offset:4640
	ds_read_b128 v[24:27], v59 offset:3904
	ds_read_b128 v[28:31], v59 offset:3936
	ds_read_b128 v[170:173], v59 offset:4672
	ds_read_b128 v[174:177], v59 offset:4704
	ds_read_b128 v[178:181], v59 offset:3968
	ds_read_b128 v[182:185], v59 offset:4000
	ds_read_b128 v[186:189], v59 offset:4736
	ds_read_b128 v[190:193], v59 offset:4768
	ds_read_b128 v[194:197], v59 offset:4032
	ds_read_b128 v[198:201], v59 offset:4064
	ds_read_b128 v[202:205], v59 offset:4800
	ds_read_b128 v[206:209], v59 offset:4832
	s_waitcnt lgkmcnt(14)
	v_pk_fma_f32 v[18:19], v[2:3], v[18:19], 0 op_sel_hi:[1,1,0]
	v_pk_fma_f32 v[16:17], v[0:1], v[16:17], 0 op_sel_hi:[1,1,0]
	s_waitcnt lgkmcnt(7)
	v_pk_fma_f32 v[180:181], v[34:35], v[180:181], 0 op_sel_hi:[1,1,0]
	v_pk_fma_f32 v[178:179], v[32:33], v[178:179], 0 op_sel_hi:[1,1,0]
	v_pk_fma_f32 v[18:19], v[6:7], v[22:23], v[18:19]
	v_pk_fma_f32 v[16:17], v[4:5], v[20:21], v[16:17]
	s_waitcnt lgkmcnt(6)
	v_pk_fma_f32 v[20:21], v[38:39], v[184:185], v[180:181]
	v_pk_fma_f32 v[22:23], v[36:37], v[182:183], v[178:179]
	v_pk_fma_f32 v[16:17], v[8:9], v[24:25], v[16:17]
	v_pk_fma_f32 v[18:19], v[10:11], v[26:27], v[18:19]
	s_waitcnt lgkmcnt(3)
	v_pk_fma_f32 v[22:23], v[40:41], v[194:195], v[22:23]
	v_pk_fma_f32 v[20:21], v[42:43], v[196:197], v[20:21]
	v_pk_fma_f32 v[18:19], v[14:15], v[30:31], v[18:19]
	v_pk_fma_f32 v[16:17], v[12:13], v[28:29], v[16:17]
	s_waitcnt lgkmcnt(2)
	v_pk_fma_f32 v[20:21], v[46:47], v[200:201], v[20:21]
	v_pk_fma_f32 v[22:23], v[44:45], v[198:199], v[22:23]
	v_add_f32_e32 v16, v16, v17
	v_add_f32_e32 v17, v18, v19
	v_add_u32_e32 v159, 0x1000, v61
	v_add_f32_e32 v16, v16, v17
	v_add_f32_e32 v17, v22, v23
	v_add_f32_e32 v18, v20, v21
	ds_read2_b32 v[210:211], v159 offset1:32
	ds_read_b32 v159, v158 offset:4864
	ds_read_b64 v[194:195], v50 offset:20760
	v_add_f32_e32 v17, v17, v18
	v_add_f32_e32 v16, v16, v17
	v_mov_b32_e32 v17, v16
	s_nop 1
	v_permlane32_swap_b32_e32 v16, v17
	v_add_f32_e32 v161, v16, v17
	s_waitcnt lgkmcnt(0)
	v_cndmask_b32_e64 v178, v159, v161, s[6:7]
	v_pk_fma_f32 v[164:165], v[2:3], v[164:165], 0 op_sel_hi:[1,1,0]
	v_pk_fma_f32 v[162:163], v[0:1], v[162:163], 0 op_sel_hi:[1,1,0]
	v_mfma_f32_32x32x2_f32 v[16:31], v211, v178, v[32:47]
	v_pk_fma_f32 v[34:35], v[34:35], v[188:189], 0 op_sel_hi:[1,1,0]
	v_pk_fma_f32 v[32:33], v[32:33], v[186:187], 0 op_sel_hi:[1,1,0]
	v_pk_fma_f32 v[164:165], v[6:7], v[168:169], v[164:165]
	v_pk_fma_f32 v[162:163], v[4:5], v[166:167], v[162:163]
	v_pk_fma_f32 v[34:35], v[38:39], v[192:193], v[34:35]
	v_pk_fma_f32 v[32:33], v[36:37], v[190:191], v[32:33]
	v_pk_fma_f32 v[36:37], v[8:9], v[170:171], v[162:163]
	v_pk_fma_f32 v[38:39], v[10:11], v[172:173], v[164:165]
	v_pk_fma_f32 v[36:37], v[12:13], v[174:175], v[36:37]
	v_pk_fma_f32 v[38:39], v[14:15], v[176:177], v[38:39]
	v_pk_fma_f32 v[32:33], v[40:41], v[202:203], v[32:33]
	v_pk_fma_f32 v[34:35], v[42:43], v[204:205], v[34:35]
	v_pk_fma_f32 v[32:33], v[44:45], v[206:207], v[32:33]
	v_pk_fma_f32 v[34:35], v[46:47], v[208:209], v[34:35]
	v_add_f32_e32 v36, v36, v37
	v_mfma_f32_32x32x2_f32 v[0:15], v210, v178, v[0:15]
	v_add_f32_e32 v37, v38, v39
	v_add_f32_e32 v32, v32, v33
	v_add_f32_e32 v33, v34, v35
	v_add_f32_e32 v36, v36, v37
	v_add_f32_e32 v32, v32, v33
	v_add_f32_e32 v32, v36, v32
	v_mov_b32_e32 v34, v32
	s_nop 1
	v_permlane32_swap_b32_e32 v32, v34
	s_and_saveexec_b64 s[28:29], s[6:7]
	s_cbranch_execz .LBB0_509
	s_add_i32 s39, s26, 3
	s_add_i32 s41, s30, 36
	s_and_b64 s[34:35], s[8:9], exec
	s_cselect_b32 s34, s39, s41
	s_waitcnt lgkmcnt(0)
	v_mul_f32_e32 v35, v161, v194
	v_mul_f32_e32 v33, v159, v195
	v_pk_add_f32 v[32:33], v[32:33], v[34:35]
	s_ashr_i32 s35, s34, 31
	v_add_f32_e32 v34, v32, v33
	v_lshl_add_u64 v[32:33], v[66:67], 0, s[34:35]
	v_lshlrev_b64 v[32:33], 11, v[32:33]
	v_lshl_add_u64 v[32:33], v[68:69], 0, v[32:33]
	global_store_dword v[32:33], v34, off
.LBB0_509:
	s_or_b64 exec, exec, s[28:29]
	ds_read_b128 v[34:37], v59 offset:5120
	ds_read_b128 v[38:41], v59 offset:5152
	ds_read_b128 v[42:45], v59 offset:5888
	ds_read_b128 v[162:165], v59 offset:5920
	ds_read_b128 v[166:169], v59 offset:5184
	ds_read_b128 v[170:173], v59 offset:5216
	ds_read_b128 v[174:177], v59 offset:5952
	ds_read_b128 v[178:181], v59 offset:5984
	ds_read_b128 v[182:185], v59 offset:5248
	ds_read_b128 v[186:189], v59 offset:5280
	ds_read_b128 v[190:193], v59 offset:5312
	ds_read_b128 v[194:197], v59 offset:5344
	s_waitcnt lgkmcnt(11)
	v_pk_fma_f32 v[36:37], v[2:3], v[36:37], 0 op_sel_hi:[1,1,0]
	v_pk_fma_f32 v[34:35], v[0:1], v[34:35], 0 op_sel_hi:[1,1,0]
	s_waitcnt lgkmcnt(3)
	v_pk_fma_f32 v[46:47], v[18:19], v[184:185], 0 op_sel_hi:[1,1,0]
	v_pk_fma_f32 v[182:183], v[16:17], v[182:183], 0 op_sel_hi:[1,1,0]
	v_pk_fma_f32 v[36:37], v[6:7], v[40:41], v[36:37]
	v_pk_fma_f32 v[34:35], v[4:5], v[38:39], v[34:35]
	s_waitcnt lgkmcnt(2)
	v_pk_fma_f32 v[38:39], v[22:23], v[188:189], v[46:47]
	v_pk_fma_f32 v[40:41], v[20:21], v[186:187], v[182:183]
	v_pk_fma_f32 v[34:35], v[8:9], v[166:167], v[34:35]
	v_pk_fma_f32 v[36:37], v[10:11], v[168:169], v[36:37]
	s_waitcnt lgkmcnt(1)
	v_pk_fma_f32 v[38:39], v[26:27], v[192:193], v[38:39]
	v_add_u32_e32 v32, 0x1400, v61
	v_pk_fma_f32 v[40:41], v[24:25], v[190:191], v[40:41]
	v_pk_fma_f32 v[36:37], v[14:15], v[172:173], v[36:37]
	v_pk_fma_f32 v[34:35], v[12:13], v[170:171], v[34:35]
	s_waitcnt lgkmcnt(0)
	v_pk_fma_f32 v[38:39], v[30:31], v[196:197], v[38:39]
	ds_read2_b32 v[198:199], v32 offset0:64 offset1:96
	ds_read_b32 v33, v158 offset:6144
	ds_read_b64 v[170:171], v50 offset:20768
	v_pk_fma_f32 v[40:41], v[28:29], v[194:195], v[40:41]
	v_add_f32_e32 v32, v34, v35
	v_add_f32_e32 v34, v36, v37
	v_add_f32_e32 v35, v38, v39
	v_pk_fma_f32 v[36:37], v[2:3], v[44:45], 0 op_sel_hi:[1,1,0]
	v_pk_fma_f32 v[38:39], v[0:1], v[42:43], 0 op_sel_hi:[1,1,0]
	v_add_f32_e32 v32, v32, v34
	v_add_f32_e32 v34, v40, v41
	v_pk_fma_f32 v[36:37], v[6:7], v[164:165], v[36:37]
	v_pk_fma_f32 v[38:39], v[4:5], v[162:163], v[38:39]
	v_add_f32_e32 v34, v34, v35
	v_pk_fma_f32 v[38:39], v[8:9], v[174:175], v[38:39]
	v_pk_fma_f32 v[36:37], v[10:11], v[176:177], v[36:37]
	v_add_f32_e32 v32, v32, v34
	v_pk_fma_f32 v[166:167], v[14:15], v[180:181], v[36:37]
	v_pk_fma_f32 v[168:169], v[12:13], v[178:179], v[38:39]
	ds_read_b128 v[36:39], v59 offset:6016
	ds_read_b128 v[40:43], v59 offset:6048
	ds_read_b128 v[44:47], v59 offset:6080
	ds_read_b128 v[162:165], v59 offset:6112
	v_mov_b32_e32 v34, v32
	s_nop 1
	v_permlane32_swap_b32_e32 v32, v34
	s_waitcnt lgkmcnt(3)
	v_pk_fma_f32 v[38:39], v[18:19], v[38:39], 0 op_sel_hi:[1,1,0]
	v_pk_fma_f32 v[36:37], v[16:17], v[36:37], 0 op_sel_hi:[1,1,0]
	v_add_f32_e32 v35, v32, v34
	s_waitcnt lgkmcnt(2)
	v_pk_fma_f32 v[38:39], v[22:23], v[42:43], v[38:39]
	v_pk_fma_f32 v[36:37], v[20:21], v[40:41], v[36:37]
	v_cndmask_b32_e64 v32, v33, v35, s[6:7]
	s_waitcnt lgkmcnt(1)
	v_pk_fma_f32 v[36:37], v[24:25], v[44:45], v[36:37]
	v_pk_fma_f32 v[38:39], v[26:27], v[46:47], v[38:39]
	v_mfma_f32_32x32x2_f32 v[0:15], v198, v32, v[0:15]
	s_waitcnt lgkmcnt(0)
	v_pk_fma_f32 v[38:39], v[30:31], v[164:165], v[38:39]
	v_pk_fma_f32 v[36:37], v[28:29], v[162:163], v[36:37]
	v_add_f32_e32 v34, v166, v167
	v_mfma_f32_32x32x2_f32 v[16:31], v199, v32, v[16:31]
	v_add_f32_e32 v32, v168, v169
	v_add_f32_e32 v32, v32, v34
	v_add_f32_e32 v34, v36, v37
	v_add_f32_e32 v36, v38, v39
	v_add_f32_e32 v34, v34, v36
	v_add_f32_e32 v32, v32, v34
	v_mov_b32_e32 v34, v32
	s_nop 1
	v_permlane32_swap_b32_e32 v32, v34
	s_and_saveexec_b64 s[28:29], s[6:7]
	s_cbranch_execz .LBB0_511
	s_add_i32 s39, s26, 4
	s_add_i32 s41, s30, 35
	s_and_b64 s[34:35], s[8:9], exec
	s_cselect_b32 s34, s39, s41
	s_waitcnt lgkmcnt(0)
	v_mul_f32_e32 v35, v35, v170
	v_mul_f32_e32 v33, v33, v171
	v_pk_add_f32 v[32:33], v[32:33], v[34:35]
	s_ashr_i32 s35, s34, 31
	v_add_f32_e32 v34, v32, v33
	v_lshl_add_u64 v[32:33], v[66:67], 0, s[34:35]
	v_lshlrev_b64 v[32:33], 11, v[32:33]
	v_lshl_add_u64 v[32:33], v[68:69], 0, v[32:33]
	global_store_dword v[32:33], v34, off
.LBB0_511:
	s_or_b64 exec, exec, s[28:29]
	ds_read_b128 v[32:35], v59 offset:6400
	ds_read_b128 v[36:39], v59 offset:6432
	ds_read_b128 v[162:165], v59 offset:7168
	ds_read_b128 v[166:169], v59 offset:7200
	ds_read_b128 v[40:43], v59 offset:6464
	ds_read_b128 v[44:47], v59 offset:6496
	ds_read_b128 v[170:173], v59 offset:7232
	ds_read_b128 v[174:177], v59 offset:7264
	ds_read_b128 v[178:181], v59 offset:6528
	ds_read_b128 v[182:185], v59 offset:6560
	ds_read_b128 v[186:189], v59 offset:7296
	ds_read_b128 v[190:193], v59 offset:7328
	ds_read_b128 v[194:197], v59 offset:6592
	ds_read_b128 v[198:201], v59 offset:6624
	ds_read_b128 v[202:205], v59 offset:7360
	ds_read_b128 v[206:209], v59 offset:7392
	s_waitcnt lgkmcnt(14)
	v_pk_fma_f32 v[34:35], v[2:3], v[34:35], 0 op_sel_hi:[1,1,0]
	v_pk_fma_f32 v[32:33], v[0:1], v[32:33], 0 op_sel_hi:[1,1,0]
	s_waitcnt lgkmcnt(7)
	v_pk_fma_f32 v[180:181], v[18:19], v[180:181], 0 op_sel_hi:[1,1,0]
	v_pk_fma_f32 v[178:179], v[16:17], v[178:179], 0 op_sel_hi:[1,1,0]
	v_pk_fma_f32 v[34:35], v[6:7], v[38:39], v[34:35]
	v_pk_fma_f32 v[32:33], v[4:5], v[36:37], v[32:33]
	s_waitcnt lgkmcnt(6)
	v_pk_fma_f32 v[36:37], v[22:23], v[184:185], v[180:181]
	v_pk_fma_f32 v[38:39], v[20:21], v[182:183], v[178:179]
	v_pk_fma_f32 v[32:33], v[8:9], v[40:41], v[32:33]
	v_pk_fma_f32 v[34:35], v[10:11], v[42:43], v[34:35]
	s_waitcnt lgkmcnt(3)
	v_pk_fma_f32 v[38:39], v[24:25], v[194:195], v[38:39]
	v_pk_fma_f32 v[36:37], v[26:27], v[196:197], v[36:37]
	v_pk_fma_f32 v[34:35], v[14:15], v[46:47], v[34:35]
	v_pk_fma_f32 v[32:33], v[12:13], v[44:45], v[32:33]
	s_waitcnt lgkmcnt(2)
	v_pk_fma_f32 v[36:37], v[30:31], v[200:201], v[36:37]
	v_pk_fma_f32 v[38:39], v[28:29], v[198:199], v[38:39]
	v_add_f32_e32 v32, v32, v33
	v_add_f32_e32 v33, v34, v35
	v_add_u32_e32 v159, 0x1800, v61
	v_add_f32_e32 v32, v32, v33
	v_add_f32_e32 v33, v38, v39
	v_add_f32_e32 v34, v36, v37
	ds_read2_b32 v[210:211], v159 offset0:128 offset1:160
	ds_read_b32 v159, v158 offset:7424
	ds_read_b64 v[194:195], v50 offset:20776
	v_add_f32_e32 v33, v33, v34
	v_add_f32_e32 v32, v32, v33
	v_mov_b32_e32 v33, v32
	s_nop 1
	v_permlane32_swap_b32_e32 v32, v33
	v_add_f32_e32 v161, v32, v33
	s_waitcnt lgkmcnt(0)
	v_cndmask_b32_e64 v178, v159, v161, s[6:7]
	v_pk_fma_f32 v[164:165], v[2:3], v[164:165], 0 op_sel_hi:[1,1,0]
	v_pk_fma_f32 v[162:163], v[0:1], v[162:163], 0 op_sel_hi:[1,1,0]
	v_mfma_f32_32x32x2_f32 v[32:47], v211, v178, v[16:31]
	v_pk_fma_f32 v[18:19], v[18:19], v[188:189], 0 op_sel_hi:[1,1,0]
	v_pk_fma_f32 v[16:17], v[16:17], v[186:187], 0 op_sel_hi:[1,1,0]
	v_pk_fma_f32 v[164:165], v[6:7], v[168:169], v[164:165]
	v_pk_fma_f32 v[162:163], v[4:5], v[166:167], v[162:163]
	v_pk_fma_f32 v[18:19], v[22:23], v[192:193], v[18:19]
	v_pk_fma_f32 v[16:17], v[20:21], v[190:191], v[16:17]
	v_pk_fma_f32 v[20:21], v[8:9], v[170:171], v[162:163]
	v_pk_fma_f32 v[22:23], v[10:11], v[172:173], v[164:165]
	v_pk_fma_f32 v[20:21], v[12:13], v[174:175], v[20:21]
	v_pk_fma_f32 v[22:23], v[14:15], v[176:177], v[22:23]
	v_pk_fma_f32 v[16:17], v[24:25], v[202:203], v[16:17]
	v_pk_fma_f32 v[18:19], v[26:27], v[204:205], v[18:19]
	v_pk_fma_f32 v[16:17], v[28:29], v[206:207], v[16:17]
	v_pk_fma_f32 v[18:19], v[30:31], v[208:209], v[18:19]
	v_add_f32_e32 v20, v20, v21
	v_mfma_f32_32x32x2_f32 v[0:15], v210, v178, v[0:15]
	v_add_f32_e32 v21, v22, v23
	v_add_f32_e32 v16, v16, v17
	v_add_f32_e32 v17, v18, v19
	v_add_f32_e32 v20, v20, v21
	v_add_f32_e32 v16, v16, v17
	v_add_f32_e32 v16, v20, v16
	v_mov_b32_e32 v18, v16
	s_nop 1
	v_permlane32_swap_b32_e32 v16, v18
	s_and_saveexec_b64 s[28:29], s[6:7]
	s_cbranch_execz .LBB0_513
	s_add_i32 s39, s26, 5
	s_add_i32 s41, s30, 34
	s_and_b64 s[34:35], s[8:9], exec
	s_cselect_b32 s34, s39, s41
	s_waitcnt lgkmcnt(0)
	v_mul_f32_e32 v19, v161, v194
	v_mul_f32_e32 v17, v159, v195
	v_pk_add_f32 v[16:17], v[16:17], v[18:19]
	s_ashr_i32 s35, s34, 31
	v_add_f32_e32 v18, v16, v17
	v_lshl_add_u64 v[16:17], v[66:67], 0, s[34:35]
	v_lshlrev_b64 v[16:17], 11, v[16:17]
	v_lshl_add_u64 v[16:17], v[68:69], 0, v[16:17]
	global_store_dword v[16:17], v18, off
.LBB0_513:
	s_or_b64 exec, exec, s[28:29]
	ds_read_b128 v[18:21], v59 offset:7680
	ds_read_b128 v[22:25], v59 offset:7712
	ds_read_b128 v[26:29], v59 offset:8448
	ds_read_b128 v[162:165], v59 offset:8480
	ds_read_b128 v[166:169], v59 offset:7744
	ds_read_b128 v[170:173], v59 offset:7776
	ds_read_b128 v[174:177], v59 offset:8512
	ds_read_b128 v[178:181], v59 offset:8544
	ds_read_b128 v[182:185], v59 offset:7808
	ds_read_b128 v[186:189], v59 offset:7840
	ds_read_b128 v[190:193], v59 offset:7872
	ds_read_b128 v[194:197], v59 offset:7904
	s_waitcnt lgkmcnt(11)
	v_pk_fma_f32 v[20:21], v[2:3], v[20:21], 0 op_sel_hi:[1,1,0]
	v_pk_fma_f32 v[18:19], v[0:1], v[18:19], 0 op_sel_hi:[1,1,0]
	s_waitcnt lgkmcnt(3)
	v_pk_fma_f32 v[30:31], v[34:35], v[184:185], 0 op_sel_hi:[1,1,0]
	v_pk_fma_f32 v[182:183], v[32:33], v[182:183], 0 op_sel_hi:[1,1,0]
	v_pk_fma_f32 v[20:21], v[6:7], v[24:25], v[20:21]
	v_pk_fma_f32 v[18:19], v[4:5], v[22:23], v[18:19]
	s_waitcnt lgkmcnt(2)
	v_pk_fma_f32 v[22:23], v[38:39], v[188:189], v[30:31]
	v_pk_fma_f32 v[24:25], v[36:37], v[186:187], v[182:183]
	v_pk_fma_f32 v[18:19], v[8:9], v[166:167], v[18:19]
	v_pk_fma_f32 v[20:21], v[10:11], v[168:169], v[20:21]
	s_waitcnt lgkmcnt(1)
	v_pk_fma_f32 v[22:23], v[42:43], v[192:193], v[22:23]
	v_add_u32_e32 v16, 0x1c00, v61
	v_pk_fma_f32 v[24:25], v[40:41], v[190:191], v[24:25]
	v_pk_fma_f32 v[20:21], v[14:15], v[172:173], v[20:21]
	v_pk_fma_f32 v[18:19], v[12:13], v[170:171], v[18:19]
	s_waitcnt lgkmcnt(0)
	v_pk_fma_f32 v[22:23], v[46:47], v[196:197], v[22:23]
	ds_read2_b32 v[198:199], v16 offset0:192 offset1:224
	ds_read_b32 v17, v158 offset:8704
	ds_read_b64 v[170:171], v50 offset:20784
	v_pk_fma_f32 v[24:25], v[44:45], v[194:195], v[24:25]
	v_add_f32_e32 v16, v18, v19
	v_add_f32_e32 v18, v20, v21
	v_add_f32_e32 v19, v22, v23
	v_pk_fma_f32 v[20:21], v[2:3], v[28:29], 0 op_sel_hi:[1,1,0]
	v_pk_fma_f32 v[22:23], v[0:1], v[26:27], 0 op_sel_hi:[1,1,0]
	v_add_f32_e32 v16, v16, v18
	v_add_f32_e32 v18, v24, v25
	v_pk_fma_f32 v[20:21], v[6:7], v[164:165], v[20:21]
	v_pk_fma_f32 v[22:23], v[4:5], v[162:163], v[22:23]
	v_add_f32_e32 v18, v18, v19
	v_pk_fma_f32 v[22:23], v[8:9], v[174:175], v[22:23]
	v_pk_fma_f32 v[20:21], v[10:11], v[176:177], v[20:21]
	v_add_f32_e32 v16, v16, v18
	v_pk_fma_f32 v[166:167], v[14:15], v[180:181], v[20:21]
	v_pk_fma_f32 v[168:169], v[12:13], v[178:179], v[22:23]
	ds_read_b128 v[20:23], v59 offset:8576
	ds_read_b128 v[24:27], v59 offset:8608
	ds_read_b128 v[28:31], v59 offset:8640
	ds_read_b128 v[162:165], v59 offset:8672
	v_mov_b32_e32 v18, v16
	s_nop 1
	v_permlane32_swap_b32_e32 v16, v18
	s_waitcnt lgkmcnt(3)
	v_pk_fma_f32 v[22:23], v[34:35], v[22:23], 0 op_sel_hi:[1,1,0]
	v_pk_fma_f32 v[20:21], v[32:33], v[20:21], 0 op_sel_hi:[1,1,0]
	v_add_f32_e32 v19, v16, v18
	s_waitcnt lgkmcnt(2)
	v_pk_fma_f32 v[22:23], v[38:39], v[26:27], v[22:23]
	v_pk_fma_f32 v[20:21], v[36:37], v[24:25], v[20:21]
	v_cndmask_b32_e64 v16, v17, v19, s[6:7]
	s_waitcnt lgkmcnt(1)
	v_pk_fma_f32 v[20:21], v[40:41], v[28:29], v[20:21]
	v_pk_fma_f32 v[22:23], v[42:43], v[30:31], v[22:23]
	v_mfma_f32_32x32x2_f32 v[0:15], v198, v16, v[0:15]
	s_waitcnt lgkmcnt(0)
	v_pk_fma_f32 v[22:23], v[46:47], v[164:165], v[22:23]
	v_pk_fma_f32 v[20:21], v[44:45], v[162:163], v[20:21]
	v_add_f32_e32 v18, v166, v167
	v_mfma_f32_32x32x2_f32 v[32:47], v199, v16, v[32:47]
	v_add_f32_e32 v16, v168, v169
	v_add_f32_e32 v16, v16, v18
	v_add_f32_e32 v18, v20, v21
	v_add_f32_e32 v20, v22, v23
	v_add_f32_e32 v18, v18, v20
	v_add_f32_e32 v16, v16, v18
	v_mov_b32_e32 v18, v16
	s_nop 1
	v_permlane32_swap_b32_e32 v16, v18
	s_and_saveexec_b64 s[28:29], s[6:7]
	s_cbranch_execz .LBB0_515
	s_add_i32 s39, s26, 6
	s_add_i32 s41, s30, 33
	s_and_b64 s[34:35], s[8:9], exec
	s_cselect_b32 s34, s39, s41
	s_waitcnt lgkmcnt(0)
	v_mul_f32_e32 v19, v19, v170
	v_mul_f32_e32 v17, v17, v171
	v_pk_add_f32 v[16:17], v[16:17], v[18:19]
	s_ashr_i32 s35, s34, 31
	v_add_f32_e32 v18, v16, v17
	v_lshl_add_u64 v[16:17], v[66:67], 0, s[34:35]
	v_lshlrev_b64 v[16:17], 11, v[16:17]
	v_lshl_add_u64 v[16:17], v[68:69], 0, v[16:17]
	global_store_dword v[16:17], v18, off
.LBB0_515:
	s_or_b64 exec, exec, s[28:29]
	ds_read_b128 v[16:19], v59 offset:8960
	ds_read_b128 v[20:23], v59 offset:8992
	ds_read_b128 v[162:165], v59 offset:9728
	ds_read_b128 v[166:169], v59 offset:9760
	ds_read_b128 v[24:27], v59 offset:9024
	ds_read_b128 v[28:31], v59 offset:9056
	ds_read_b128 v[170:173], v59 offset:9792
	ds_read_b128 v[174:177], v59 offset:9824
	ds_read_b128 v[178:181], v59 offset:9088
	ds_read_b128 v[182:185], v59 offset:9120
	ds_read_b128 v[186:189], v59 offset:9856
	ds_read_b128 v[190:193], v59 offset:9888
	ds_read_b128 v[194:197], v59 offset:9152
	ds_read_b128 v[198:201], v59 offset:9184
	ds_read_b128 v[202:205], v59 offset:9920
	ds_read_b128 v[206:209], v59 offset:9952
	s_waitcnt lgkmcnt(14)
	v_pk_fma_f32 v[18:19], v[2:3], v[18:19], 0 op_sel_hi:[1,1,0]
	v_pk_fma_f32 v[16:17], v[0:1], v[16:17], 0 op_sel_hi:[1,1,0]
	s_waitcnt lgkmcnt(7)
	v_pk_fma_f32 v[180:181], v[34:35], v[180:181], 0 op_sel_hi:[1,1,0]
	v_pk_fma_f32 v[178:179], v[32:33], v[178:179], 0 op_sel_hi:[1,1,0]
	v_pk_fma_f32 v[18:19], v[6:7], v[22:23], v[18:19]
	v_pk_fma_f32 v[16:17], v[4:5], v[20:21], v[16:17]
	s_waitcnt lgkmcnt(6)
	v_pk_fma_f32 v[20:21], v[38:39], v[184:185], v[180:181]
	v_pk_fma_f32 v[22:23], v[36:37], v[182:183], v[178:179]
	v_pk_fma_f32 v[16:17], v[8:9], v[24:25], v[16:17]
	v_pk_fma_f32 v[18:19], v[10:11], v[26:27], v[18:19]
	s_waitcnt lgkmcnt(3)
	v_pk_fma_f32 v[22:23], v[40:41], v[194:195], v[22:23]
	v_pk_fma_f32 v[20:21], v[42:43], v[196:197], v[20:21]
	v_pk_fma_f32 v[18:19], v[14:15], v[30:31], v[18:19]
	v_pk_fma_f32 v[16:17], v[12:13], v[28:29], v[16:17]
	s_waitcnt lgkmcnt(2)
	v_pk_fma_f32 v[20:21], v[46:47], v[200:201], v[20:21]
	v_pk_fma_f32 v[22:23], v[44:45], v[198:199], v[22:23]
	v_add_f32_e32 v16, v16, v17
	v_add_f32_e32 v17, v18, v19
	v_add_u32_e32 v159, 0x2400, v61
	v_add_f32_e32 v16, v16, v17
	v_add_f32_e32 v17, v22, v23
	v_add_f32_e32 v18, v20, v21
	ds_read2_b32 v[210:211], v159 offset1:32
	ds_read_b32 v159, v158 offset:9984
	ds_read_b64 v[194:195], v50 offset:20792
	v_add_f32_e32 v17, v17, v18
	v_add_f32_e32 v16, v16, v17
	v_mov_b32_e32 v17, v16
	s_nop 1
	v_permlane32_swap_b32_e32 v16, v17
	v_add_f32_e32 v161, v16, v17
	s_waitcnt lgkmcnt(0)
	v_cndmask_b32_e64 v178, v159, v161, s[6:7]
	v_pk_fma_f32 v[164:165], v[2:3], v[164:165], 0 op_sel_hi:[1,1,0]
	v_pk_fma_f32 v[162:163], v[0:1], v[162:163], 0 op_sel_hi:[1,1,0]
	v_mfma_f32_32x32x2_f32 v[16:31], v211, v178, v[32:47]
	v_pk_fma_f32 v[34:35], v[34:35], v[188:189], 0 op_sel_hi:[1,1,0]
	v_pk_fma_f32 v[32:33], v[32:33], v[186:187], 0 op_sel_hi:[1,1,0]
	v_pk_fma_f32 v[164:165], v[6:7], v[168:169], v[164:165]
	v_pk_fma_f32 v[162:163], v[4:5], v[166:167], v[162:163]
	v_pk_fma_f32 v[34:35], v[38:39], v[192:193], v[34:35]
	v_pk_fma_f32 v[32:33], v[36:37], v[190:191], v[32:33]
	v_pk_fma_f32 v[36:37], v[8:9], v[170:171], v[162:163]
	v_pk_fma_f32 v[38:39], v[10:11], v[172:173], v[164:165]
	v_pk_fma_f32 v[36:37], v[12:13], v[174:175], v[36:37]
	v_pk_fma_f32 v[38:39], v[14:15], v[176:177], v[38:39]
	v_pk_fma_f32 v[32:33], v[40:41], v[202:203], v[32:33]
	v_pk_fma_f32 v[34:35], v[42:43], v[204:205], v[34:35]
	v_pk_fma_f32 v[32:33], v[44:45], v[206:207], v[32:33]
	v_pk_fma_f32 v[34:35], v[46:47], v[208:209], v[34:35]
	v_add_f32_e32 v36, v36, v37
	v_mfma_f32_32x32x2_f32 v[0:15], v210, v178, v[0:15]
	v_add_f32_e32 v37, v38, v39
	v_add_f32_e32 v32, v32, v33
	v_add_f32_e32 v33, v34, v35
	v_add_f32_e32 v36, v36, v37
	v_add_f32_e32 v32, v32, v33
	v_add_f32_e32 v32, v36, v32
	v_mov_b32_e32 v34, v32
	s_nop 1
	v_permlane32_swap_b32_e32 v32, v34
	s_and_saveexec_b64 s[28:29], s[6:7]
	s_cbranch_execz .LBB0_517
	s_add_i32 s39, s26, 7
	s_add_i32 s41, s30, 32
	s_and_b64 s[34:35], s[8:9], exec
	s_cselect_b32 s34, s39, s41
	s_waitcnt lgkmcnt(0)
	v_mul_f32_e32 v35, v161, v194
	v_mul_f32_e32 v33, v159, v195
	v_pk_add_f32 v[32:33], v[32:33], v[34:35]
	s_ashr_i32 s35, s34, 31
	v_add_f32_e32 v34, v32, v33
	v_lshl_add_u64 v[32:33], v[66:67], 0, s[34:35]
	v_lshlrev_b64 v[32:33], 11, v[32:33]
	v_lshl_add_u64 v[32:33], v[68:69], 0, v[32:33]
	global_store_dword v[32:33], v34, off
.LBB0_517:
	s_or_b64 exec, exec, s[28:29]
	ds_read_b128 v[34:37], v59 offset:10240
	ds_read_b128 v[38:41], v59 offset:10272
	ds_read_b128 v[42:45], v59 offset:11008
	ds_read_b128 v[162:165], v59 offset:11040
	ds_read_b128 v[166:169], v59 offset:10304
	ds_read_b128 v[170:173], v59 offset:10336
	ds_read_b128 v[174:177], v59 offset:11072
	ds_read_b128 v[178:181], v59 offset:11104
	ds_read_b128 v[182:185], v59 offset:10368
	ds_read_b128 v[186:189], v59 offset:10400
	ds_read_b128 v[190:193], v59 offset:10432
	ds_read_b128 v[194:197], v59 offset:10464
	s_waitcnt lgkmcnt(11)
	v_pk_fma_f32 v[36:37], v[2:3], v[36:37], 0 op_sel_hi:[1,1,0]
	v_pk_fma_f32 v[34:35], v[0:1], v[34:35], 0 op_sel_hi:[1,1,0]
	s_waitcnt lgkmcnt(3)
	v_pk_fma_f32 v[46:47], v[18:19], v[184:185], 0 op_sel_hi:[1,1,0]
	v_pk_fma_f32 v[182:183], v[16:17], v[182:183], 0 op_sel_hi:[1,1,0]
	v_pk_fma_f32 v[36:37], v[6:7], v[40:41], v[36:37]
	v_pk_fma_f32 v[34:35], v[4:5], v[38:39], v[34:35]
	s_waitcnt lgkmcnt(2)
	v_pk_fma_f32 v[38:39], v[22:23], v[188:189], v[46:47]
	v_pk_fma_f32 v[40:41], v[20:21], v[186:187], v[182:183]
	v_pk_fma_f32 v[34:35], v[8:9], v[166:167], v[34:35]
	v_pk_fma_f32 v[36:37], v[10:11], v[168:169], v[36:37]
	s_waitcnt lgkmcnt(1)
	v_pk_fma_f32 v[38:39], v[26:27], v[192:193], v[38:39]
	v_add_u32_e32 v32, 0x2800, v61
	v_pk_fma_f32 v[40:41], v[24:25], v[190:191], v[40:41]
	v_pk_fma_f32 v[36:37], v[14:15], v[172:173], v[36:37]
	v_pk_fma_f32 v[34:35], v[12:13], v[170:171], v[34:35]
	s_waitcnt lgkmcnt(0)
	v_pk_fma_f32 v[38:39], v[30:31], v[196:197], v[38:39]
	ds_read2_b32 v[198:199], v32 offset0:64 offset1:96
	ds_read_b32 v33, v158 offset:11264
	ds_read_b64 v[170:171], v50 offset:20800
	v_pk_fma_f32 v[40:41], v[28:29], v[194:195], v[40:41]
	v_add_f32_e32 v32, v34, v35
	v_add_f32_e32 v34, v36, v37
	v_add_f32_e32 v35, v38, v39
	v_pk_fma_f32 v[36:37], v[2:3], v[44:45], 0 op_sel_hi:[1,1,0]
	v_pk_fma_f32 v[38:39], v[0:1], v[42:43], 0 op_sel_hi:[1,1,0]
	v_add_f32_e32 v32, v32, v34
	v_add_f32_e32 v34, v40, v41
	v_pk_fma_f32 v[36:37], v[6:7], v[164:165], v[36:37]
	v_pk_fma_f32 v[38:39], v[4:5], v[162:163], v[38:39]
	v_add_f32_e32 v34, v34, v35
	v_pk_fma_f32 v[38:39], v[8:9], v[174:175], v[38:39]
	v_pk_fma_f32 v[36:37], v[10:11], v[176:177], v[36:37]
	v_add_f32_e32 v32, v32, v34
	v_pk_fma_f32 v[166:167], v[14:15], v[180:181], v[36:37]
	v_pk_fma_f32 v[168:169], v[12:13], v[178:179], v[38:39]
	ds_read_b128 v[36:39], v59 offset:11136
	ds_read_b128 v[40:43], v59 offset:11168
	ds_read_b128 v[44:47], v59 offset:11200
	ds_read_b128 v[162:165], v59 offset:11232
	v_mov_b32_e32 v34, v32
	s_nop 1
	v_permlane32_swap_b32_e32 v32, v34
	s_waitcnt lgkmcnt(3)
	v_pk_fma_f32 v[38:39], v[18:19], v[38:39], 0 op_sel_hi:[1,1,0]
	v_pk_fma_f32 v[36:37], v[16:17], v[36:37], 0 op_sel_hi:[1,1,0]
	v_add_f32_e32 v35, v32, v34
	s_waitcnt lgkmcnt(2)
	v_pk_fma_f32 v[38:39], v[22:23], v[42:43], v[38:39]
	v_pk_fma_f32 v[36:37], v[20:21], v[40:41], v[36:37]
	v_cndmask_b32_e64 v32, v33, v35, s[6:7]
	s_waitcnt lgkmcnt(1)
	v_pk_fma_f32 v[36:37], v[24:25], v[44:45], v[36:37]
	v_pk_fma_f32 v[38:39], v[26:27], v[46:47], v[38:39]
	v_mfma_f32_32x32x2_f32 v[0:15], v198, v32, v[0:15]
	s_waitcnt lgkmcnt(0)
	v_pk_fma_f32 v[38:39], v[30:31], v[164:165], v[38:39]
	v_pk_fma_f32 v[36:37], v[28:29], v[162:163], v[36:37]
	v_add_f32_e32 v34, v166, v167
	v_mfma_f32_32x32x2_f32 v[16:31], v199, v32, v[16:31]
	v_add_f32_e32 v32, v168, v169
	v_add_f32_e32 v32, v32, v34
	v_add_f32_e32 v34, v36, v37
	v_add_f32_e32 v36, v38, v39
	v_add_f32_e32 v34, v34, v36
	v_add_f32_e32 v32, v32, v34
	v_mov_b32_e32 v34, v32
	s_nop 1
	v_permlane32_swap_b32_e32 v32, v34
	s_and_saveexec_b64 s[28:29], s[6:7]
	s_cbranch_execz .LBB0_519
	s_add_i32 s39, s26, 8
	s_add_i32 s41, s30, 31
	s_and_b64 s[34:35], s[8:9], exec
	s_cselect_b32 s34, s39, s41
	s_waitcnt lgkmcnt(0)
	v_mul_f32_e32 v35, v35, v170
	v_mul_f32_e32 v33, v33, v171
	v_pk_add_f32 v[32:33], v[32:33], v[34:35]
	s_ashr_i32 s35, s34, 31
	v_add_f32_e32 v34, v32, v33
	v_lshl_add_u64 v[32:33], v[66:67], 0, s[34:35]
	v_lshlrev_b64 v[32:33], 11, v[32:33]
	v_lshl_add_u64 v[32:33], v[68:69], 0, v[32:33]
	global_store_dword v[32:33], v34, off
.LBB0_519:
	s_or_b64 exec, exec, s[28:29]
	ds_read_b128 v[32:35], v59 offset:11520
	ds_read_b128 v[36:39], v59 offset:11552
	ds_read_b128 v[162:165], v59 offset:12288
	ds_read_b128 v[166:169], v59 offset:12320
	ds_read_b128 v[40:43], v59 offset:11584
	ds_read_b128 v[44:47], v59 offset:11616
	ds_read_b128 v[170:173], v59 offset:12352
	ds_read_b128 v[174:177], v59 offset:12384
	ds_read_b128 v[178:181], v59 offset:11648
	ds_read_b128 v[182:185], v59 offset:11680
	ds_read_b128 v[186:189], v59 offset:12416
	ds_read_b128 v[190:193], v59 offset:12448
	ds_read_b128 v[194:197], v59 offset:11712
	ds_read_b128 v[198:201], v59 offset:11744
	ds_read_b128 v[202:205], v59 offset:12480
	ds_read_b128 v[206:209], v59 offset:12512
	s_waitcnt lgkmcnt(14)
	v_pk_fma_f32 v[34:35], v[2:3], v[34:35], 0 op_sel_hi:[1,1,0]
	v_pk_fma_f32 v[32:33], v[0:1], v[32:33], 0 op_sel_hi:[1,1,0]
	s_waitcnt lgkmcnt(7)
	v_pk_fma_f32 v[180:181], v[18:19], v[180:181], 0 op_sel_hi:[1,1,0]
	v_pk_fma_f32 v[178:179], v[16:17], v[178:179], 0 op_sel_hi:[1,1,0]
	v_pk_fma_f32 v[34:35], v[6:7], v[38:39], v[34:35]
	v_pk_fma_f32 v[32:33], v[4:5], v[36:37], v[32:33]
	s_waitcnt lgkmcnt(6)
	v_pk_fma_f32 v[36:37], v[22:23], v[184:185], v[180:181]
	v_pk_fma_f32 v[38:39], v[20:21], v[182:183], v[178:179]
	v_pk_fma_f32 v[32:33], v[8:9], v[40:41], v[32:33]
	v_pk_fma_f32 v[34:35], v[10:11], v[42:43], v[34:35]
	s_waitcnt lgkmcnt(3)
	v_pk_fma_f32 v[38:39], v[24:25], v[194:195], v[38:39]
	v_pk_fma_f32 v[36:37], v[26:27], v[196:197], v[36:37]
	v_pk_fma_f32 v[34:35], v[14:15], v[46:47], v[34:35]
	v_pk_fma_f32 v[32:33], v[12:13], v[44:45], v[32:33]
	s_waitcnt lgkmcnt(2)
	v_pk_fma_f32 v[36:37], v[30:31], v[200:201], v[36:37]
	v_pk_fma_f32 v[38:39], v[28:29], v[198:199], v[38:39]
	v_add_f32_e32 v32, v32, v33
	v_add_f32_e32 v33, v34, v35
	v_add_u32_e32 v159, 0x2c00, v61
	v_add_f32_e32 v32, v32, v33
	v_add_f32_e32 v33, v38, v39
	v_add_f32_e32 v34, v36, v37
	ds_read2_b32 v[210:211], v159 offset0:128 offset1:160
	ds_read_b32 v159, v158 offset:12544
	ds_read_b64 v[194:195], v50 offset:20808
	v_add_f32_e32 v33, v33, v34
	v_add_f32_e32 v32, v32, v33
	v_mov_b32_e32 v33, v32
	s_nop 1
	v_permlane32_swap_b32_e32 v32, v33
	v_add_f32_e32 v161, v32, v33
	s_waitcnt lgkmcnt(0)
	v_cndmask_b32_e64 v178, v159, v161, s[6:7]
	v_pk_fma_f32 v[164:165], v[2:3], v[164:165], 0 op_sel_hi:[1,1,0]
	v_pk_fma_f32 v[162:163], v[0:1], v[162:163], 0 op_sel_hi:[1,1,0]
	v_mfma_f32_32x32x2_f32 v[32:47], v211, v178, v[16:31]
	v_pk_fma_f32 v[18:19], v[18:19], v[188:189], 0 op_sel_hi:[1,1,0]
	v_pk_fma_f32 v[16:17], v[16:17], v[186:187], 0 op_sel_hi:[1,1,0]
	v_pk_fma_f32 v[164:165], v[6:7], v[168:169], v[164:165]
	v_pk_fma_f32 v[162:163], v[4:5], v[166:167], v[162:163]
	v_pk_fma_f32 v[18:19], v[22:23], v[192:193], v[18:19]
	v_pk_fma_f32 v[16:17], v[20:21], v[190:191], v[16:17]
	v_pk_fma_f32 v[20:21], v[8:9], v[170:171], v[162:163]
	v_pk_fma_f32 v[22:23], v[10:11], v[172:173], v[164:165]
	v_pk_fma_f32 v[20:21], v[12:13], v[174:175], v[20:21]
	v_pk_fma_f32 v[22:23], v[14:15], v[176:177], v[22:23]
	v_pk_fma_f32 v[16:17], v[24:25], v[202:203], v[16:17]
	v_pk_fma_f32 v[18:19], v[26:27], v[204:205], v[18:19]
	v_pk_fma_f32 v[16:17], v[28:29], v[206:207], v[16:17]
	v_pk_fma_f32 v[18:19], v[30:31], v[208:209], v[18:19]
	v_add_f32_e32 v20, v20, v21
	v_mfma_f32_32x32x2_f32 v[0:15], v210, v178, v[0:15]
	v_add_f32_e32 v21, v22, v23
	v_add_f32_e32 v16, v16, v17
	v_add_f32_e32 v17, v18, v19
	v_add_f32_e32 v20, v20, v21
	v_add_f32_e32 v16, v16, v17
	v_add_f32_e32 v16, v20, v16
	v_mov_b32_e32 v18, v16
	s_nop 1
	v_permlane32_swap_b32_e32 v16, v18
	s_and_saveexec_b64 s[28:29], s[6:7]
	s_cbranch_execz .LBB0_521
	s_add_i32 s39, s26, 9
	s_add_i32 s41, s30, 30
	s_and_b64 s[34:35], s[8:9], exec
	s_cselect_b32 s34, s39, s41
	s_waitcnt lgkmcnt(0)
	v_mul_f32_e32 v19, v161, v194
	v_mul_f32_e32 v17, v159, v195
	v_pk_add_f32 v[16:17], v[16:17], v[18:19]
	s_ashr_i32 s35, s34, 31
	v_add_f32_e32 v18, v16, v17
	v_lshl_add_u64 v[16:17], v[66:67], 0, s[34:35]
	v_lshlrev_b64 v[16:17], 11, v[16:17]
	v_lshl_add_u64 v[16:17], v[68:69], 0, v[16:17]
	global_store_dword v[16:17], v18, off
.LBB0_521:
	s_or_b64 exec, exec, s[28:29]
	ds_read_b128 v[18:21], v59 offset:12800
	ds_read_b128 v[22:25], v59 offset:12832
	ds_read_b128 v[26:29], v59 offset:13568
	ds_read_b128 v[162:165], v59 offset:13600
	ds_read_b128 v[166:169], v59 offset:12864
	ds_read_b128 v[170:173], v59 offset:12896
	ds_read_b128 v[174:177], v59 offset:13632
	ds_read_b128 v[178:181], v59 offset:13664
	ds_read_b128 v[182:185], v59 offset:12928
	ds_read_b128 v[186:189], v59 offset:12960
	ds_read_b128 v[190:193], v59 offset:12992
	ds_read_b128 v[194:197], v59 offset:13024
	s_waitcnt lgkmcnt(11)
	v_pk_fma_f32 v[20:21], v[2:3], v[20:21], 0 op_sel_hi:[1,1,0]
	v_pk_fma_f32 v[18:19], v[0:1], v[18:19], 0 op_sel_hi:[1,1,0]
	s_waitcnt lgkmcnt(3)
	v_pk_fma_f32 v[30:31], v[34:35], v[184:185], 0 op_sel_hi:[1,1,0]
	v_pk_fma_f32 v[182:183], v[32:33], v[182:183], 0 op_sel_hi:[1,1,0]
	v_pk_fma_f32 v[20:21], v[6:7], v[24:25], v[20:21]
	v_pk_fma_f32 v[18:19], v[4:5], v[22:23], v[18:19]
	s_waitcnt lgkmcnt(2)
	v_pk_fma_f32 v[22:23], v[38:39], v[188:189], v[30:31]
	v_pk_fma_f32 v[24:25], v[36:37], v[186:187], v[182:183]
	v_pk_fma_f32 v[18:19], v[8:9], v[166:167], v[18:19]
	v_pk_fma_f32 v[20:21], v[10:11], v[168:169], v[20:21]
	s_waitcnt lgkmcnt(1)
	v_pk_fma_f32 v[22:23], v[42:43], v[192:193], v[22:23]
	v_add_u32_e32 v16, 0x3000, v61
	v_pk_fma_f32 v[24:25], v[40:41], v[190:191], v[24:25]
	v_pk_fma_f32 v[20:21], v[14:15], v[172:173], v[20:21]
	v_pk_fma_f32 v[18:19], v[12:13], v[170:171], v[18:19]
	s_waitcnt lgkmcnt(0)
	v_pk_fma_f32 v[22:23], v[46:47], v[196:197], v[22:23]
	ds_read2_b32 v[198:199], v16 offset0:192 offset1:224
	ds_read_b32 v17, v158 offset:13824
	ds_read_b64 v[170:171], v50 offset:20816
	v_pk_fma_f32 v[24:25], v[44:45], v[194:195], v[24:25]
	v_add_f32_e32 v16, v18, v19
	v_add_f32_e32 v18, v20, v21
	v_add_f32_e32 v19, v22, v23
	v_pk_fma_f32 v[20:21], v[2:3], v[28:29], 0 op_sel_hi:[1,1,0]
	v_pk_fma_f32 v[22:23], v[0:1], v[26:27], 0 op_sel_hi:[1,1,0]
	v_add_f32_e32 v16, v16, v18
	v_add_f32_e32 v18, v24, v25
	v_pk_fma_f32 v[20:21], v[6:7], v[164:165], v[20:21]
	v_pk_fma_f32 v[22:23], v[4:5], v[162:163], v[22:23]
	v_add_f32_e32 v18, v18, v19
	v_pk_fma_f32 v[22:23], v[8:9], v[174:175], v[22:23]
	v_pk_fma_f32 v[20:21], v[10:11], v[176:177], v[20:21]
	v_add_f32_e32 v16, v16, v18
	v_pk_fma_f32 v[166:167], v[14:15], v[180:181], v[20:21]
	v_pk_fma_f32 v[168:169], v[12:13], v[178:179], v[22:23]
	ds_read_b128 v[20:23], v59 offset:13696
	ds_read_b128 v[24:27], v59 offset:13728
	ds_read_b128 v[28:31], v59 offset:13760
	ds_read_b128 v[162:165], v59 offset:13792
	v_mov_b32_e32 v18, v16
	s_nop 1
	v_permlane32_swap_b32_e32 v16, v18
	s_waitcnt lgkmcnt(3)
	v_pk_fma_f32 v[22:23], v[34:35], v[22:23], 0 op_sel_hi:[1,1,0]
	v_pk_fma_f32 v[20:21], v[32:33], v[20:21], 0 op_sel_hi:[1,1,0]
	v_add_f32_e32 v19, v16, v18
	s_waitcnt lgkmcnt(2)
	v_pk_fma_f32 v[22:23], v[38:39], v[26:27], v[22:23]
	v_pk_fma_f32 v[20:21], v[36:37], v[24:25], v[20:21]
	v_cndmask_b32_e64 v16, v17, v19, s[6:7]
	s_waitcnt lgkmcnt(1)
	v_pk_fma_f32 v[20:21], v[40:41], v[28:29], v[20:21]
	v_pk_fma_f32 v[22:23], v[42:43], v[30:31], v[22:23]
	v_mfma_f32_32x32x2_f32 v[0:15], v198, v16, v[0:15]
	s_waitcnt lgkmcnt(0)
	v_pk_fma_f32 v[22:23], v[46:47], v[164:165], v[22:23]
	v_pk_fma_f32 v[20:21], v[44:45], v[162:163], v[20:21]
	v_add_f32_e32 v18, v166, v167
	v_mfma_f32_32x32x2_f32 v[32:47], v199, v16, v[32:47]
	v_add_f32_e32 v16, v168, v169
	v_add_f32_e32 v16, v16, v18
	v_add_f32_e32 v18, v20, v21
	v_add_f32_e32 v20, v22, v23
	v_add_f32_e32 v18, v18, v20
	v_add_f32_e32 v16, v16, v18
	v_mov_b32_e32 v18, v16
	s_nop 1
	v_permlane32_swap_b32_e32 v16, v18
	s_and_saveexec_b64 s[28:29], s[6:7]
	s_cbranch_execz .LBB0_523
	s_add_i32 s39, s26, 10
	s_add_i32 s41, s30, 29
	s_and_b64 s[34:35], s[8:9], exec
	s_cselect_b32 s34, s39, s41
	s_waitcnt lgkmcnt(0)
	v_mul_f32_e32 v19, v19, v170
	v_mul_f32_e32 v17, v17, v171
	v_pk_add_f32 v[16:17], v[16:17], v[18:19]
	s_ashr_i32 s35, s34, 31
	v_add_f32_e32 v18, v16, v17
	v_lshl_add_u64 v[16:17], v[66:67], 0, s[34:35]
	v_lshlrev_b64 v[16:17], 11, v[16:17]
	v_lshl_add_u64 v[16:17], v[68:69], 0, v[16:17]
	global_store_dword v[16:17], v18, off
.LBB0_523:
	s_or_b64 exec, exec, s[28:29]
	ds_read_b128 v[16:19], v59 offset:14080
	ds_read_b128 v[20:23], v59 offset:14112
	ds_read_b128 v[162:165], v59 offset:14848
	ds_read_b128 v[166:169], v59 offset:14880
	ds_read_b128 v[24:27], v59 offset:14144
	ds_read_b128 v[28:31], v59 offset:14176
	ds_read_b128 v[170:173], v59 offset:14912
	ds_read_b128 v[174:177], v59 offset:14944
	ds_read_b128 v[178:181], v59 offset:14208
	ds_read_b128 v[182:185], v59 offset:14240
	ds_read_b128 v[186:189], v59 offset:14976
	ds_read_b128 v[190:193], v59 offset:15008
	ds_read_b128 v[194:197], v59 offset:14272
	ds_read_b128 v[198:201], v59 offset:14304
	ds_read_b128 v[202:205], v59 offset:15040
	ds_read_b128 v[206:209], v59 offset:15072
	s_waitcnt lgkmcnt(14)
	v_pk_fma_f32 v[18:19], v[2:3], v[18:19], 0 op_sel_hi:[1,1,0]
	v_pk_fma_f32 v[16:17], v[0:1], v[16:17], 0 op_sel_hi:[1,1,0]
	s_waitcnt lgkmcnt(7)
	v_pk_fma_f32 v[180:181], v[34:35], v[180:181], 0 op_sel_hi:[1,1,0]
	v_pk_fma_f32 v[178:179], v[32:33], v[178:179], 0 op_sel_hi:[1,1,0]
	v_pk_fma_f32 v[18:19], v[6:7], v[22:23], v[18:19]
	v_pk_fma_f32 v[16:17], v[4:5], v[20:21], v[16:17]
	s_waitcnt lgkmcnt(6)
	v_pk_fma_f32 v[20:21], v[38:39], v[184:185], v[180:181]
	v_pk_fma_f32 v[22:23], v[36:37], v[182:183], v[178:179]
	v_pk_fma_f32 v[16:17], v[8:9], v[24:25], v[16:17]
	v_pk_fma_f32 v[18:19], v[10:11], v[26:27], v[18:19]
	s_waitcnt lgkmcnt(3)
	v_pk_fma_f32 v[22:23], v[40:41], v[194:195], v[22:23]
	v_pk_fma_f32 v[20:21], v[42:43], v[196:197], v[20:21]
	v_pk_fma_f32 v[18:19], v[14:15], v[30:31], v[18:19]
	v_pk_fma_f32 v[16:17], v[12:13], v[28:29], v[16:17]
	s_waitcnt lgkmcnt(2)
	v_pk_fma_f32 v[20:21], v[46:47], v[200:201], v[20:21]
	v_pk_fma_f32 v[22:23], v[44:45], v[198:199], v[22:23]
	v_add_f32_e32 v16, v16, v17
	v_add_f32_e32 v17, v18, v19
	v_add_u32_e32 v159, 0x3800, v61
	v_add_f32_e32 v16, v16, v17
	v_add_f32_e32 v17, v22, v23
	v_add_f32_e32 v18, v20, v21
	ds_read2_b32 v[210:211], v159 offset1:32
	ds_read_b32 v159, v158 offset:15104
	ds_read_b64 v[194:195], v50 offset:20824
	v_add_f32_e32 v17, v17, v18
	v_add_f32_e32 v16, v16, v17
	v_mov_b32_e32 v17, v16
	s_nop 1
	v_permlane32_swap_b32_e32 v16, v17
	v_add_f32_e32 v161, v16, v17
	s_waitcnt lgkmcnt(0)
	v_cndmask_b32_e64 v178, v159, v161, s[6:7]
	v_pk_fma_f32 v[164:165], v[2:3], v[164:165], 0 op_sel_hi:[1,1,0]
	v_pk_fma_f32 v[162:163], v[0:1], v[162:163], 0 op_sel_hi:[1,1,0]
	v_mfma_f32_32x32x2_f32 v[16:31], v211, v178, v[32:47]
	v_pk_fma_f32 v[34:35], v[34:35], v[188:189], 0 op_sel_hi:[1,1,0]
	v_pk_fma_f32 v[32:33], v[32:33], v[186:187], 0 op_sel_hi:[1,1,0]
	v_pk_fma_f32 v[164:165], v[6:7], v[168:169], v[164:165]
	v_pk_fma_f32 v[162:163], v[4:5], v[166:167], v[162:163]
	v_pk_fma_f32 v[34:35], v[38:39], v[192:193], v[34:35]
	v_pk_fma_f32 v[32:33], v[36:37], v[190:191], v[32:33]
	v_pk_fma_f32 v[36:37], v[8:9], v[170:171], v[162:163]
	v_pk_fma_f32 v[38:39], v[10:11], v[172:173], v[164:165]
	v_pk_fma_f32 v[36:37], v[12:13], v[174:175], v[36:37]
	v_pk_fma_f32 v[38:39], v[14:15], v[176:177], v[38:39]
	v_pk_fma_f32 v[32:33], v[40:41], v[202:203], v[32:33]
	v_pk_fma_f32 v[34:35], v[42:43], v[204:205], v[34:35]
	v_pk_fma_f32 v[32:33], v[44:45], v[206:207], v[32:33]
	v_pk_fma_f32 v[34:35], v[46:47], v[208:209], v[34:35]
	v_add_f32_e32 v36, v36, v37
	v_mfma_f32_32x32x2_f32 v[0:15], v210, v178, v[0:15]
	v_add_f32_e32 v37, v38, v39
	v_add_f32_e32 v32, v32, v33
	v_add_f32_e32 v33, v34, v35
	v_add_f32_e32 v36, v36, v37
	v_add_f32_e32 v32, v32, v33
	v_add_f32_e32 v32, v36, v32
	v_mov_b32_e32 v34, v32
	s_nop 1
	v_permlane32_swap_b32_e32 v32, v34
	s_and_saveexec_b64 s[28:29], s[6:7]
	s_cbranch_execz .LBB0_525
	s_add_i32 s39, s26, 11
	s_add_i32 s41, s30, 28
	s_and_b64 s[34:35], s[8:9], exec
	s_cselect_b32 s34, s39, s41
	s_waitcnt lgkmcnt(0)
	v_mul_f32_e32 v35, v161, v194
	v_mul_f32_e32 v33, v159, v195
	v_pk_add_f32 v[32:33], v[32:33], v[34:35]
	s_ashr_i32 s35, s34, 31
	v_add_f32_e32 v34, v32, v33
	v_lshl_add_u64 v[32:33], v[66:67], 0, s[34:35]
	v_lshlrev_b64 v[32:33], 11, v[32:33]
	v_lshl_add_u64 v[32:33], v[68:69], 0, v[32:33]
	global_store_dword v[32:33], v34, off
.LBB0_525:
	s_or_b64 exec, exec, s[28:29]
	ds_read_b128 v[34:37], v59 offset:15360
	ds_read_b128 v[38:41], v59 offset:15392
	ds_read_b128 v[42:45], v59 offset:16128
	ds_read_b128 v[162:165], v59 offset:16160
	ds_read_b128 v[166:169], v59 offset:15424
	ds_read_b128 v[170:173], v59 offset:15456
	ds_read_b128 v[174:177], v59 offset:16192
	ds_read_b128 v[178:181], v59 offset:16224
	ds_read_b128 v[182:185], v59 offset:15488
	ds_read_b128 v[186:189], v59 offset:15520
	ds_read_b128 v[190:193], v59 offset:15552
	ds_read_b128 v[194:197], v59 offset:15584
	s_waitcnt lgkmcnt(11)
	v_pk_fma_f32 v[36:37], v[2:3], v[36:37], 0 op_sel_hi:[1,1,0]
	v_pk_fma_f32 v[34:35], v[0:1], v[34:35], 0 op_sel_hi:[1,1,0]
	s_waitcnt lgkmcnt(3)
	v_pk_fma_f32 v[46:47], v[18:19], v[184:185], 0 op_sel_hi:[1,1,0]
	v_pk_fma_f32 v[182:183], v[16:17], v[182:183], 0 op_sel_hi:[1,1,0]
	v_pk_fma_f32 v[36:37], v[6:7], v[40:41], v[36:37]
	v_pk_fma_f32 v[34:35], v[4:5], v[38:39], v[34:35]
	s_waitcnt lgkmcnt(2)
	v_pk_fma_f32 v[38:39], v[22:23], v[188:189], v[46:47]
	v_pk_fma_f32 v[40:41], v[20:21], v[186:187], v[182:183]
	v_pk_fma_f32 v[34:35], v[8:9], v[166:167], v[34:35]
	v_pk_fma_f32 v[36:37], v[10:11], v[168:169], v[36:37]
	s_waitcnt lgkmcnt(1)
	v_pk_fma_f32 v[38:39], v[26:27], v[192:193], v[38:39]
	v_add_u32_e32 v32, 0x3c00, v61
	v_pk_fma_f32 v[40:41], v[24:25], v[190:191], v[40:41]
	v_pk_fma_f32 v[36:37], v[14:15], v[172:173], v[36:37]
	v_pk_fma_f32 v[34:35], v[12:13], v[170:171], v[34:35]
	s_waitcnt lgkmcnt(0)
	v_pk_fma_f32 v[38:39], v[30:31], v[196:197], v[38:39]
	ds_read2_b32 v[198:199], v32 offset0:64 offset1:96
	ds_read_b32 v33, v158 offset:16384
	ds_read_b64 v[170:171], v50 offset:20832
	v_pk_fma_f32 v[40:41], v[28:29], v[194:195], v[40:41]
	v_add_f32_e32 v32, v34, v35
	v_add_f32_e32 v34, v36, v37
	v_add_f32_e32 v35, v38, v39
	v_pk_fma_f32 v[36:37], v[2:3], v[44:45], 0 op_sel_hi:[1,1,0]
	v_pk_fma_f32 v[38:39], v[0:1], v[42:43], 0 op_sel_hi:[1,1,0]
	v_add_f32_e32 v32, v32, v34
	v_add_f32_e32 v34, v40, v41
	v_pk_fma_f32 v[36:37], v[6:7], v[164:165], v[36:37]
	v_pk_fma_f32 v[38:39], v[4:5], v[162:163], v[38:39]
	v_add_f32_e32 v34, v34, v35
	v_pk_fma_f32 v[38:39], v[8:9], v[174:175], v[38:39]
	v_pk_fma_f32 v[36:37], v[10:11], v[176:177], v[36:37]
	v_add_f32_e32 v32, v32, v34
	v_pk_fma_f32 v[166:167], v[14:15], v[180:181], v[36:37]
	v_pk_fma_f32 v[168:169], v[12:13], v[178:179], v[38:39]
	ds_read_b128 v[36:39], v59 offset:16256
	ds_read_b128 v[40:43], v59 offset:16288
	ds_read_b128 v[44:47], v59 offset:16320
	ds_read_b128 v[162:165], v59 offset:16352
	v_mov_b32_e32 v34, v32
	s_nop 1
	v_permlane32_swap_b32_e32 v32, v34
	s_waitcnt lgkmcnt(3)
	v_pk_fma_f32 v[38:39], v[18:19], v[38:39], 0 op_sel_hi:[1,1,0]
	v_pk_fma_f32 v[36:37], v[16:17], v[36:37], 0 op_sel_hi:[1,1,0]
	v_add_f32_e32 v35, v32, v34
	s_waitcnt lgkmcnt(2)
	v_pk_fma_f32 v[38:39], v[22:23], v[42:43], v[38:39]
	v_pk_fma_f32 v[36:37], v[20:21], v[40:41], v[36:37]
	v_cndmask_b32_e64 v32, v33, v35, s[6:7]
	s_waitcnt lgkmcnt(1)
	v_pk_fma_f32 v[36:37], v[24:25], v[44:45], v[36:37]
	v_pk_fma_f32 v[38:39], v[26:27], v[46:47], v[38:39]
	v_mfma_f32_32x32x2_f32 v[0:15], v198, v32, v[0:15]
	s_waitcnt lgkmcnt(0)
	v_pk_fma_f32 v[38:39], v[30:31], v[164:165], v[38:39]
	v_pk_fma_f32 v[36:37], v[28:29], v[162:163], v[36:37]
	v_add_f32_e32 v34, v166, v167
	v_mfma_f32_32x32x2_f32 v[16:31], v199, v32, v[16:31]
	v_add_f32_e32 v32, v168, v169
	v_add_f32_e32 v32, v32, v34
	v_add_f32_e32 v34, v36, v37
	v_add_f32_e32 v36, v38, v39
	v_add_f32_e32 v34, v34, v36
	v_add_f32_e32 v32, v32, v34
	v_mov_b32_e32 v34, v32
	s_nop 1
	v_permlane32_swap_b32_e32 v32, v34
	s_and_saveexec_b64 s[28:29], s[6:7]
	s_cbranch_execz .LBB0_527
	s_add_i32 s39, s26, 12
	s_add_i32 s41, s30, 27
	s_and_b64 s[34:35], s[8:9], exec
	s_cselect_b32 s34, s39, s41
	s_waitcnt lgkmcnt(0)
	v_mul_f32_e32 v35, v35, v170
	v_mul_f32_e32 v33, v33, v171
	v_pk_add_f32 v[32:33], v[32:33], v[34:35]
	s_ashr_i32 s35, s34, 31
	v_add_f32_e32 v34, v32, v33
	v_lshl_add_u64 v[32:33], v[66:67], 0, s[34:35]
	v_lshlrev_b64 v[32:33], 11, v[32:33]
	v_lshl_add_u64 v[32:33], v[68:69], 0, v[32:33]
	global_store_dword v[32:33], v34, off
.LBB0_527:
	s_or_b64 exec, exec, s[28:29]
	ds_read_b128 v[32:35], v59 offset:16640
	ds_read_b128 v[36:39], v59 offset:16672
	ds_read_b128 v[162:165], v59 offset:17408
	ds_read_b128 v[166:169], v59 offset:17440
	ds_read_b128 v[40:43], v59 offset:16704
	ds_read_b128 v[44:47], v59 offset:16736
	ds_read_b128 v[170:173], v59 offset:17472
	ds_read_b128 v[174:177], v59 offset:17504
	ds_read_b128 v[178:181], v59 offset:16768
	ds_read_b128 v[182:185], v59 offset:16800
	ds_read_b128 v[186:189], v59 offset:17536
	ds_read_b128 v[190:193], v59 offset:17568
	ds_read_b128 v[194:197], v59 offset:16832
	ds_read_b128 v[198:201], v59 offset:16864
	ds_read_b128 v[202:205], v59 offset:17600
	ds_read_b128 v[206:209], v59 offset:17632
	s_waitcnt lgkmcnt(14)
	v_pk_fma_f32 v[34:35], v[2:3], v[34:35], 0 op_sel_hi:[1,1,0]
	v_pk_fma_f32 v[32:33], v[0:1], v[32:33], 0 op_sel_hi:[1,1,0]
	s_waitcnt lgkmcnt(7)
	v_pk_fma_f32 v[180:181], v[18:19], v[180:181], 0 op_sel_hi:[1,1,0]
	v_pk_fma_f32 v[178:179], v[16:17], v[178:179], 0 op_sel_hi:[1,1,0]
	v_pk_fma_f32 v[34:35], v[6:7], v[38:39], v[34:35]
	v_pk_fma_f32 v[32:33], v[4:5], v[36:37], v[32:33]
	s_waitcnt lgkmcnt(6)
	v_pk_fma_f32 v[36:37], v[22:23], v[184:185], v[180:181]
	v_pk_fma_f32 v[38:39], v[20:21], v[182:183], v[178:179]
	v_pk_fma_f32 v[32:33], v[8:9], v[40:41], v[32:33]
	v_pk_fma_f32 v[34:35], v[10:11], v[42:43], v[34:35]
	s_waitcnt lgkmcnt(3)
	v_pk_fma_f32 v[38:39], v[24:25], v[194:195], v[38:39]
	v_pk_fma_f32 v[36:37], v[26:27], v[196:197], v[36:37]
	v_pk_fma_f32 v[34:35], v[14:15], v[46:47], v[34:35]
	v_pk_fma_f32 v[32:33], v[12:13], v[44:45], v[32:33]
	s_waitcnt lgkmcnt(2)
	v_pk_fma_f32 v[36:37], v[30:31], v[200:201], v[36:37]
	v_pk_fma_f32 v[38:39], v[28:29], v[198:199], v[38:39]
	v_add_f32_e32 v32, v32, v33
	v_add_f32_e32 v33, v34, v35
	v_add_u32_e32 v159, 0x4000, v61
	v_add_f32_e32 v32, v32, v33
	v_add_f32_e32 v33, v38, v39
	v_add_f32_e32 v34, v36, v37
	ds_read2_b32 v[210:211], v159 offset0:128 offset1:160
	ds_read_b32 v159, v158 offset:17664
	ds_read_b64 v[194:195], v50 offset:20840
	v_add_f32_e32 v33, v33, v34
	v_add_f32_e32 v32, v32, v33
	v_mov_b32_e32 v33, v32
	s_nop 1
	v_permlane32_swap_b32_e32 v32, v33
	v_add_f32_e32 v161, v32, v33
	s_waitcnt lgkmcnt(0)
	v_cndmask_b32_e64 v178, v159, v161, s[6:7]
	v_pk_fma_f32 v[164:165], v[2:3], v[164:165], 0 op_sel_hi:[1,1,0]
	v_pk_fma_f32 v[162:163], v[0:1], v[162:163], 0 op_sel_hi:[1,1,0]
	v_mfma_f32_32x32x2_f32 v[32:47], v211, v178, v[16:31]
	v_pk_fma_f32 v[18:19], v[18:19], v[188:189], 0 op_sel_hi:[1,1,0]
	v_pk_fma_f32 v[16:17], v[16:17], v[186:187], 0 op_sel_hi:[1,1,0]
	v_pk_fma_f32 v[164:165], v[6:7], v[168:169], v[164:165]
	v_pk_fma_f32 v[162:163], v[4:5], v[166:167], v[162:163]
	v_pk_fma_f32 v[18:19], v[22:23], v[192:193], v[18:19]
	v_pk_fma_f32 v[16:17], v[20:21], v[190:191], v[16:17]
	v_pk_fma_f32 v[20:21], v[8:9], v[170:171], v[162:163]
	v_pk_fma_f32 v[22:23], v[10:11], v[172:173], v[164:165]
	v_pk_fma_f32 v[20:21], v[12:13], v[174:175], v[20:21]
	v_pk_fma_f32 v[22:23], v[14:15], v[176:177], v[22:23]
	v_pk_fma_f32 v[16:17], v[24:25], v[202:203], v[16:17]
	v_pk_fma_f32 v[18:19], v[26:27], v[204:205], v[18:19]
	v_pk_fma_f32 v[16:17], v[28:29], v[206:207], v[16:17]
	v_pk_fma_f32 v[18:19], v[30:31], v[208:209], v[18:19]
	v_add_f32_e32 v20, v20, v21
	v_mfma_f32_32x32x2_f32 v[0:15], v210, v178, v[0:15]
	v_add_f32_e32 v21, v22, v23
	v_add_f32_e32 v16, v16, v17
	v_add_f32_e32 v17, v18, v19
	v_add_f32_e32 v20, v20, v21
	v_add_f32_e32 v16, v16, v17
	v_add_f32_e32 v16, v20, v16
	v_mov_b32_e32 v18, v16
	s_nop 1
	v_permlane32_swap_b32_e32 v16, v18
	s_and_saveexec_b64 s[28:29], s[6:7]
	s_cbranch_execz .LBB0_529
	s_add_i32 s39, s26, 13
	s_add_i32 s41, s30, 26
	s_and_b64 s[34:35], s[8:9], exec
	s_cselect_b32 s34, s39, s41
	s_waitcnt lgkmcnt(0)
	v_mul_f32_e32 v19, v161, v194
	v_mul_f32_e32 v17, v159, v195
	v_pk_add_f32 v[16:17], v[16:17], v[18:19]
	s_ashr_i32 s35, s34, 31
	v_add_f32_e32 v18, v16, v17
	v_lshl_add_u64 v[16:17], v[66:67], 0, s[34:35]
	v_lshlrev_b64 v[16:17], 11, v[16:17]
	v_lshl_add_u64 v[16:17], v[68:69], 0, v[16:17]
	global_store_dword v[16:17], v18, off
.LBB0_529:
	s_or_b64 exec, exec, s[28:29]
	ds_read_b128 v[18:21], v59 offset:17920
	ds_read_b128 v[22:25], v59 offset:17952
	ds_read_b128 v[26:29], v59 offset:18688
	ds_read_b128 v[162:165], v59 offset:18720
	ds_read_b128 v[166:169], v59 offset:17984
	ds_read_b128 v[170:173], v59 offset:18016
	ds_read_b128 v[174:177], v59 offset:18752
	ds_read_b128 v[178:181], v59 offset:18784
	ds_read_b128 v[182:185], v59 offset:18048
	ds_read_b128 v[186:189], v59 offset:18080
	ds_read_b128 v[190:193], v59 offset:18112
	ds_read_b128 v[194:197], v59 offset:18144
	s_waitcnt lgkmcnt(11)
	v_pk_fma_f32 v[20:21], v[2:3], v[20:21], 0 op_sel_hi:[1,1,0]
	v_pk_fma_f32 v[18:19], v[0:1], v[18:19], 0 op_sel_hi:[1,1,0]
	s_waitcnt lgkmcnt(3)
	v_pk_fma_f32 v[30:31], v[34:35], v[184:185], 0 op_sel_hi:[1,1,0]
	v_pk_fma_f32 v[182:183], v[32:33], v[182:183], 0 op_sel_hi:[1,1,0]
	v_pk_fma_f32 v[20:21], v[6:7], v[24:25], v[20:21]
	v_pk_fma_f32 v[18:19], v[4:5], v[22:23], v[18:19]
	s_waitcnt lgkmcnt(2)
	v_pk_fma_f32 v[22:23], v[38:39], v[188:189], v[30:31]
	v_pk_fma_f32 v[24:25], v[36:37], v[186:187], v[182:183]
	v_pk_fma_f32 v[18:19], v[8:9], v[166:167], v[18:19]
	v_pk_fma_f32 v[20:21], v[10:11], v[168:169], v[20:21]
	s_waitcnt lgkmcnt(1)
	v_pk_fma_f32 v[22:23], v[42:43], v[192:193], v[22:23]
	v_add_u32_e32 v16, 0x4400, v61
	v_pk_fma_f32 v[24:25], v[40:41], v[190:191], v[24:25]
	v_pk_fma_f32 v[20:21], v[14:15], v[172:173], v[20:21]
	v_pk_fma_f32 v[18:19], v[12:13], v[170:171], v[18:19]
	s_waitcnt lgkmcnt(0)
	v_pk_fma_f32 v[22:23], v[46:47], v[196:197], v[22:23]
	ds_read2_b32 v[198:199], v16 offset0:192 offset1:224
	ds_read_b32 v17, v158 offset:18944
	ds_read_b64 v[170:171], v50 offset:20848
	v_pk_fma_f32 v[24:25], v[44:45], v[194:195], v[24:25]
	v_add_f32_e32 v16, v18, v19
	v_add_f32_e32 v18, v20, v21
	v_add_f32_e32 v19, v22, v23
	v_pk_fma_f32 v[20:21], v[2:3], v[28:29], 0 op_sel_hi:[1,1,0]
	v_pk_fma_f32 v[22:23], v[0:1], v[26:27], 0 op_sel_hi:[1,1,0]
	v_add_f32_e32 v16, v16, v18
	v_add_f32_e32 v18, v24, v25
	v_pk_fma_f32 v[20:21], v[6:7], v[164:165], v[20:21]
	v_pk_fma_f32 v[22:23], v[4:5], v[162:163], v[22:23]
	v_add_f32_e32 v18, v18, v19
	v_pk_fma_f32 v[22:23], v[8:9], v[174:175], v[22:23]
	v_pk_fma_f32 v[20:21], v[10:11], v[176:177], v[20:21]
	v_add_f32_e32 v16, v16, v18
	v_pk_fma_f32 v[166:167], v[14:15], v[180:181], v[20:21]
	v_pk_fma_f32 v[168:169], v[12:13], v[178:179], v[22:23]
	ds_read_b128 v[20:23], v59 offset:18816
	ds_read_b128 v[24:27], v59 offset:18848
	ds_read_b128 v[28:31], v59 offset:18880
	ds_read_b128 v[162:165], v59 offset:18912
	v_mov_b32_e32 v18, v16
	s_nop 1
	v_permlane32_swap_b32_e32 v16, v18
	s_waitcnt lgkmcnt(3)
	v_pk_fma_f32 v[22:23], v[34:35], v[22:23], 0 op_sel_hi:[1,1,0]
	v_pk_fma_f32 v[20:21], v[32:33], v[20:21], 0 op_sel_hi:[1,1,0]
	v_add_f32_e32 v19, v16, v18
	s_waitcnt lgkmcnt(2)
	v_pk_fma_f32 v[22:23], v[38:39], v[26:27], v[22:23]
	v_pk_fma_f32 v[20:21], v[36:37], v[24:25], v[20:21]
	v_cndmask_b32_e64 v16, v17, v19, s[6:7]
	s_waitcnt lgkmcnt(1)
	v_pk_fma_f32 v[20:21], v[40:41], v[28:29], v[20:21]
	v_pk_fma_f32 v[22:23], v[42:43], v[30:31], v[22:23]
	v_mfma_f32_32x32x2_f32 v[0:15], v198, v16, v[0:15]
	s_waitcnt lgkmcnt(0)
	v_pk_fma_f32 v[22:23], v[46:47], v[164:165], v[22:23]
	v_pk_fma_f32 v[20:21], v[44:45], v[162:163], v[20:21]
	v_add_f32_e32 v18, v166, v167
	v_mfma_f32_32x32x2_f32 v[32:47], v199, v16, v[32:47]
	v_add_f32_e32 v16, v168, v169
	v_add_f32_e32 v16, v16, v18
	v_add_f32_e32 v18, v20, v21
	v_add_f32_e32 v20, v22, v23
	v_add_f32_e32 v18, v18, v20
	v_add_f32_e32 v16, v16, v18
	v_mov_b32_e32 v18, v16
	s_nop 1
	v_permlane32_swap_b32_e32 v16, v18
	s_and_saveexec_b64 s[28:29], s[6:7]
	s_cbranch_execz .LBB0_531
	s_add_i32 s39, s26, 14
	s_add_i32 s41, s30, 25
	s_and_b64 s[34:35], s[8:9], exec
	s_cselect_b32 s34, s39, s41
	s_waitcnt lgkmcnt(0)
	v_mul_f32_e32 v19, v19, v170
	v_mul_f32_e32 v17, v17, v171
	v_pk_add_f32 v[16:17], v[16:17], v[18:19]
	s_ashr_i32 s35, s34, 31
	v_add_f32_e32 v18, v16, v17
	v_lshl_add_u64 v[16:17], v[66:67], 0, s[34:35]
	v_lshlrev_b64 v[16:17], 11, v[16:17]
	v_lshl_add_u64 v[16:17], v[68:69], 0, v[16:17]
	global_store_dword v[16:17], v18, off
.LBB0_531:
	s_or_b64 exec, exec, s[28:29]
	ds_read_b128 v[16:19], v59 offset:19200
	ds_read_b128 v[20:23], v59 offset:19232
	ds_read_b128 v[162:165], v59 offset:19968
	ds_read_b128 v[166:169], v59 offset:20000
	ds_read_b128 v[24:27], v59 offset:19264
	ds_read_b128 v[28:31], v59 offset:19296
	ds_read_b128 v[170:173], v59 offset:20032
	ds_read_b128 v[174:177], v59 offset:20064
	ds_read_b128 v[178:181], v59 offset:19328
	ds_read_b128 v[182:185], v59 offset:19360
	ds_read_b128 v[186:189], v59 offset:20096
	ds_read_b128 v[190:193], v59 offset:20128
	ds_read_b128 v[194:197], v59 offset:19392
	ds_read_b128 v[198:201], v59 offset:19424
	ds_read_b128 v[202:205], v59 offset:20160
	ds_read_b128 v[206:209], v59 offset:20192
	v_add_u32_e32 v59, 0x4c00, v61
	s_waitcnt lgkmcnt(14)
	v_pk_fma_f32 v[18:19], v[2:3], v[18:19], 0 op_sel_hi:[1,1,0]
	v_pk_fma_f32 v[16:17], v[0:1], v[16:17], 0 op_sel_hi:[1,1,0]
	ds_read2_b32 v[210:211], v59 offset1:32
	ds_read_b32 v59, v158 offset:20224
	s_waitcnt lgkmcnt(9)
	v_pk_fma_f32 v[158:159], v[34:35], v[180:181], 0 op_sel_hi:[1,1,0]
	v_pk_fma_f32 v[178:179], v[32:33], v[178:179], 0 op_sel_hi:[1,1,0]
	v_pk_fma_f32 v[18:19], v[6:7], v[22:23], v[18:19]
	v_pk_fma_f32 v[16:17], v[4:5], v[20:21], v[16:17]
	s_waitcnt lgkmcnt(8)
	v_pk_fma_f32 v[20:21], v[38:39], v[184:185], v[158:159]
	v_pk_fma_f32 v[22:23], v[36:37], v[182:183], v[178:179]
	v_pk_fma_f32 v[16:17], v[8:9], v[24:25], v[16:17]
	v_pk_fma_f32 v[18:19], v[10:11], v[26:27], v[18:19]
	s_waitcnt lgkmcnt(5)
	v_pk_fma_f32 v[22:23], v[40:41], v[194:195], v[22:23]
	v_pk_fma_f32 v[20:21], v[42:43], v[196:197], v[20:21]
	v_pk_fma_f32 v[18:19], v[14:15], v[30:31], v[18:19]
	v_pk_fma_f32 v[16:17], v[12:13], v[28:29], v[16:17]
	s_waitcnt lgkmcnt(4)
	v_pk_fma_f32 v[20:21], v[46:47], v[200:201], v[20:21]
	v_pk_fma_f32 v[22:23], v[44:45], v[198:199], v[22:23]
	v_add_f32_e32 v16, v16, v17
	v_add_f32_e32 v17, v18, v19
	v_add_f32_e32 v16, v16, v17
	v_add_f32_e32 v17, v22, v23
	v_add_f32_e32 v18, v20, v21
	v_add_f32_e32 v17, v17, v18
	v_add_f32_e32 v16, v16, v17
	v_mov_b32_e32 v17, v16
	s_nop 1
	v_permlane32_swap_b32_e32 v16, v17
	v_add_f32_e32 v61, v16, v17
	s_waitcnt lgkmcnt(0)
	v_cndmask_b32_e64 v161, v59, v61, s[6:7]
	v_pk_fma_f32 v[158:159], v[2:3], v[164:165], 0 op_sel_hi:[1,1,0]
	v_pk_fma_f32 v[162:163], v[0:1], v[162:163], 0 op_sel_hi:[1,1,0]
	v_mfma_f32_32x32x2_f32 v[16:31], v211, v161, v[32:47]
	v_pk_fma_f32 v[34:35], v[34:35], v[188:189], 0 op_sel_hi:[1,1,0]
	v_pk_fma_f32 v[32:33], v[32:33], v[186:187], 0 op_sel_hi:[1,1,0]
	v_pk_fma_f32 v[158:159], v[6:7], v[168:169], v[158:159]
	v_pk_fma_f32 v[162:163], v[4:5], v[166:167], v[162:163]
	v_pk_fma_f32 v[34:35], v[38:39], v[192:193], v[34:35]
	v_pk_fma_f32 v[32:33], v[36:37], v[190:191], v[32:33]
	v_pk_fma_f32 v[36:37], v[8:9], v[170:171], v[162:163]
	v_pk_fma_f32 v[38:39], v[10:11], v[172:173], v[158:159]
	v_pk_fma_f32 v[36:37], v[12:13], v[174:175], v[36:37]
	v_pk_fma_f32 v[38:39], v[14:15], v[176:177], v[38:39]
	v_pk_fma_f32 v[32:33], v[40:41], v[202:203], v[32:33]
	v_pk_fma_f32 v[34:35], v[42:43], v[204:205], v[34:35]
	v_pk_fma_f32 v[32:33], v[44:45], v[206:207], v[32:33]
	v_pk_fma_f32 v[34:35], v[46:47], v[208:209], v[34:35]
	v_add_f32_e32 v36, v36, v37
	v_mfma_f32_32x32x2_f32 v[0:15], v210, v161, v[0:15]
	v_add_f32_e32 v37, v38, v39
	v_add_f32_e32 v32, v32, v33
	v_add_f32_e32 v33, v34, v35
	v_add_f32_e32 v36, v36, v37
	v_add_f32_e32 v32, v32, v33
	v_add_f32_e32 v32, v36, v32
	v_mov_b32_e32 v34, v32
	s_nop 1
	v_permlane32_swap_b32_e32 v32, v34
	s_and_saveexec_b64 s[28:29], s[6:7]
	s_cbranch_execz .LBB0_533
	ds_read_b64 v[36:37], v50 offset:20856
	s_add_i32 s39, s26, 15
	s_add_i32 s41, s30, 24
	s_and_b64 s[34:35], s[8:9], exec
	s_cselect_b32 s34, s39, s41
	s_waitcnt lgkmcnt(0)
	v_mul_f32_e32 v35, v61, v36
	v_mul_f32_e32 v33, v59, v37
	v_pk_add_f32 v[32:33], v[32:33], v[34:35]
	s_ashr_i32 s35, s34, 31
	v_add_f32_e32 v34, v32, v33
	v_lshl_add_u64 v[32:33], v[66:67], 0, s[34:35]
	v_lshlrev_b64 v[32:33], 11, v[32:33]
	v_lshl_add_u64 v[32:33], v[68:69], 0, v[32:33]
	global_store_dword v[32:33], v34, off
